# NA: threshold test on the two chain maxima separately (no dependent max->cmp tail in the common path)
# speedup vs baseline: 1.0075x; 1.0075x over previous
.Lna_wloop:
	s_sub_i32 s36, s24, s23
	s_cmp_lt_u32 s36, s63
	s_cselect_b64 s[40:41], -1, 0
	s_add_i32 s36, s36, 1
	s_cmp_lt_u32 s36, 8
	s_cselect_b64 s[44:45], -1, 0
	s_sub_i32 s37, s36, s62
	s_cmp_lt_u32 s37, 8
	s_cselect_b64 s[46:47], -1, 0
	s_and_b64 s[48:49], s[44:45], s[64:65]
	s_andn2_b64 s[38:39], s[46:47], s[64:65]
	s_or_b64 s[48:49], s[48:49], s[38:39]
	s_or_b64 s[42:43], s[44:45], s[46:47]
	s_and_b64 s[44:45], s[44:45], s[46:47]
	s_and_b64 s[44:45], s[44:45], s[40:41]
	s_cmp_eq_u64 s[44:45], 0
	s_cbranch_scc1 .Lna_slow_w1
	ds_read_b128 v[146:149], v199 offset:0
	ds_read_b128 v[150:153], v199 offset:32
	ds_read_b128 v[154:157], v199 offset:64
	ds_read_b128 v[158:161], v199 offset:96
	v_add_u32_e32 v210, s25, v208
	v_exp_f32_e32 v66, v66
	v_exp_f32_e32 v67, v67
	v_exp_f32_e32 v68, v68
	v_exp_f32_e32 v69, v69
	v_add_f32_e32 v213, v213, v66
	v_add_f32_e32 v214, v214, v67
	s_waitcnt lgkmcnt(3)
	v_mfma_f32_32x32x16_bf16 v[34:49], v[146:149], v[98:101], v[114:129]
	ds_read_b64 v[162:163], v201 offset:8704
	ds_read_b64 v[164:165], v201 offset:8720
	v_add_f32_e32 v213, v213, v68
	v_add_f32_e32 v214, v214, v69
	v_exp_f32_e32 v70, v70
	v_exp_f32_e32 v71, v71
	v_exp_f32_e32 v72, v72
	v_exp_f32_e32 v73, v73
	s_waitcnt lgkmcnt(4)
	v_mfma_f32_32x32x16_bf16 v[34:49], v[150:153], v[102:105], v[34:49]
	ds_read_b64 v[166:167], v201 offset:13056
	ds_read_b64 v[168:169], v201 offset:13072
	v_add_f32_e32 v213, v213, v70
	v_add_f32_e32 v214, v214, v71
	v_add_f32_e32 v213, v213, v72
	v_add_f32_e32 v214, v214, v73
	v_cvt_pk_bf16_f32 v66, v66, v67
	v_cvt_pk_bf16_f32 v67, v68, v69
	v_cvt_pk_bf16_f32 v68, v70, v71
	v_cvt_pk_bf16_f32 v69, v72, v73
	s_waitcnt lgkmcnt(5)
	v_mfma_f32_32x32x16_bf16 v[34:49], v[154:157], v[106:109], v[34:49]
	ds_read_b64 v[170:171], v201 offset:8736
	ds_read_b64 v[172:173], v201 offset:8752
	v_exp_f32_e32 v74, v74
	v_exp_f32_e32 v75, v75
	v_exp_f32_e32 v76, v76
	v_exp_f32_e32 v77, v77
	v_add_f32_e32 v213, v213, v74
	s_waitcnt lgkmcnt(6)
	v_mfma_f32_32x32x16_bf16 v[34:49], v[158:161], v[110:113], v[34:49]
	ds_read_b64 v[174:175], v201 offset:13088
	ds_read_b64 v[176:177], v201 offset:13104
	ds_read_b128 v[146:149], v210 offset:0
	ds_read_b128 v[150:153], v210 offset:32
	ds_read_b128 v[154:157], v210 offset:64
	ds_read_b128 v[158:161], v210 offset:96
	v_add_f32_e32 v214, v214, v75
	v_add_f32_e32 v213, v213, v76
	v_add_f32_e32 v214, v214, v77
	v_exp_f32_e32 v78, v78
	v_exp_f32_e32 v79, v79
	v_exp_f32_e32 v80, v80
	s_waitcnt lgkmcnt(10)
	v_mfma_f32_32x32x16_bf16 v[2:17], v[162:165], v[66:69], v[2:17]
	v_exp_f32_e32 v81, v81
	v_add_f32_e32 v213, v213, v78
	v_add_f32_e32 v214, v214, v79
	v_add_f32_e32 v213, v213, v80
	v_add_f32_e32 v214, v214, v81
	v_cvt_pk_bf16_f32 v74, v74, v75
	v_cvt_pk_bf16_f32 v75, v76, v77
	v_cvt_pk_bf16_f32 v76, v78, v79
	s_waitcnt lgkmcnt(8)
	v_mfma_f32_32x32x16_bf16 v[18:33], v[166:169], v[66:69], v[18:33]
	v_cvt_pk_bf16_f32 v77, v80, v81
	s_waitcnt lgkmcnt(0)
	v_add_f32_e32 v34, v34, v146
	v_add_f32_e32 v35, v35, v147
	v_add_f32_e32 v36, v36, v148
	v_add_f32_e32 v37, v37, v149
	v_add_f32_e32 v38, v38, v150
	v_add_f32_e32 v39, v39, v151
	v_add_f32_e32 v40, v40, v152
	v_add_f32_e32 v41, v41, v153
	v_mfma_f32_32x32x16_bf16 v[2:17], v[170:173], v[74:77], v[2:17]
	v_add_f32_e32 v42, v42, v154
	v_add_f32_e32 v43, v43, v155
	v_add_f32_e32 v44, v44, v156
	v_add_f32_e32 v45, v45, v157
	v_add_f32_e32 v46, v46, v158
	v_add_f32_e32 v47, v47, v159
	v_add_f32_e32 v48, v48, v160
	v_add_f32_e32 v49, v49, v161
	v_max3_f32 v216, v34, v35, v36
	v_mfma_f32_32x32x16_bf16 v[18:33], v[174:177], v[74:77], v[18:33]
	s_waitcnt vmcnt(2)
	ds_write_b128 v204, v[230:233] offset:9216
	ds_write_b64 v205, v[234:235] offset:0
	ds_write_b64 v205, v[236:237] offset:8
	global_load_dwordx4 v[230:233], v206, s[12:13]
	s_add_i32 s20, s20, 1
	s_add_u32 s12, s12, 0x2000
	s_addc_u32 s13, s13, 0
	s_cmp_eq_u32 s20, s22
	s_cselect_b32 s12, s16, s12
	s_cselect_b32 s13, s17, s13
	global_load_dwordx4 v[234:237], v207, s[14:15]
	s_add_i32 s21, s21, 1
	s_add_u32 s14, s14, 0x80
	s_addc_u32 s15, s15, 0
	s_cmp_eq_u32 s21, s22
	s_cselect_b32 s14, s18, s14
	s_cselect_b32 s15, s19, s15
	v_max3_f32 v217, v42, v43, v44
	v_max3_f32 v216, v216, v37, v38
	v_max3_f32 v217, v217, v45, v46
	v_max3_f32 v216, v216, v39, v40
	v_max3_f32 v217, v217, v47, v48
	v_max_f32_e32 v216, v216, v41
	v_max_f32_e32 v217, v217, v49
	v_cmp_lt_f32_e32 vcc, 4.0, v216
	v_cmp_lt_f32_e64 s[28:29], 4.0, v217
	s_or_b64 s[28:29], s[28:29], vcc
	s_or_b64 s[28:29], s[28:29], s[26:27]
	s_cmp_lg_u64 s[28:29], 0
	s_cbranch_scc0 .Lna_nr_w1f
	v_max_f32_e32 v216, v216, v217
	v_mov_b32_e32 v217, v216
	s_nop 1
	v_permlane32_swap_b32_e32 v216, v217
	v_max_f32_e32 v215, v216, v217
	s_nop 15
	v_max_f32_e32 v216, v215, v220
	v_cmp_lt_f32_e32 vcc, 0xf0c9f2ca, v215
	s_nop 1
	v_cndmask_b32_e32 v216, 0, v216, vcc
	v_exp_f32_e64 v217, -v216
	v_add_f32_e32 v212, v212, v216
	v_and_b32_e32 v217, v217, v221
	v_sub_f32_e32 v34, v34, v216
	v_sub_f32_e32 v35, v35, v216
	v_sub_f32_e32 v36, v36, v216
	v_sub_f32_e32 v37, v37, v216
	v_sub_f32_e32 v38, v38, v216
	v_sub_f32_e32 v39, v39, v216
	v_sub_f32_e32 v40, v40, v216
	v_sub_f32_e32 v41, v41, v216
	v_sub_f32_e32 v42, v42, v216
	v_sub_f32_e32 v43, v43, v216
	v_sub_f32_e32 v44, v44, v216
	v_sub_f32_e32 v45, v45, v216
	v_sub_f32_e32 v46, v46, v216
	v_sub_f32_e32 v47, v47, v216
	v_sub_f32_e32 v48, v48, v216
	v_sub_f32_e32 v49, v49, v216
	v_sub_f32_e32 v114, v114, v216
	v_sub_f32_e32 v115, v115, v216
	v_sub_f32_e32 v116, v116, v216
	v_sub_f32_e32 v117, v117, v216
	v_sub_f32_e32 v118, v118, v216
	v_sub_f32_e32 v119, v119, v216
	v_sub_f32_e32 v120, v120, v216
	v_sub_f32_e32 v121, v121, v216
	v_sub_f32_e32 v122, v122, v216
	v_sub_f32_e32 v123, v123, v216
	v_sub_f32_e32 v124, v124, v216
	v_sub_f32_e32 v125, v125, v216
	v_sub_f32_e32 v126, v126, v216
	v_sub_f32_e32 v127, v127, v216
	v_sub_f32_e32 v128, v128, v216
	v_sub_f32_e32 v129, v129, v216
	v_mul_f32_e32 v213, v213, v217
	v_mul_f32_e32 v214, v214, v217
	v_mul_f32_e32 v2, v2, v217
	v_mul_f32_e32 v3, v3, v217
	v_mul_f32_e32 v4, v4, v217
	v_mul_f32_e32 v5, v5, v217
	v_mul_f32_e32 v6, v6, v217
	v_mul_f32_e32 v7, v7, v217
	v_mul_f32_e32 v8, v8, v217
	v_mul_f32_e32 v9, v9, v217
	v_mul_f32_e32 v10, v10, v217
	v_mul_f32_e32 v11, v11, v217
	v_mul_f32_e32 v12, v12, v217
	v_mul_f32_e32 v13, v13, v217
	v_mul_f32_e32 v14, v14, v217
	v_mul_f32_e32 v15, v15, v217
	v_mul_f32_e32 v16, v16, v217
	v_mul_f32_e32 v17, v17, v217
	v_mul_f32_e32 v18, v18, v217
	v_mul_f32_e32 v19, v19, v217
	v_mul_f32_e32 v20, v20, v217
	v_mul_f32_e32 v21, v21, v217
	v_mul_f32_e32 v22, v22, v217
	v_mul_f32_e32 v23, v23, v217
	v_mul_f32_e32 v24, v24, v217
	v_mul_f32_e32 v25, v25, v217
	v_mul_f32_e32 v26, v26, v217
	v_mul_f32_e32 v27, v27, v217
	v_mul_f32_e32 v28, v28, v217
	v_mul_f32_e32 v29, v29, v217
	v_mul_f32_e32 v30, v30, v217
	v_mul_f32_e32 v31, v31, v217
	v_mul_f32_e32 v32, v32, v217
	v_mul_f32_e32 v33, v33, v217
	v_cndmask_b32_e32 v220, v220, v228, vcc
	v_cndmask_b32_e64 v221, v221, -1, vcc
	s_andn2_b64 s[26:27], s[26:27], vcc

.Lna_sl_a_w1s:
	s_waitcnt lgkmcnt(0)
	s_cmp_eq_u64 s[42:43], 0
	s_cbranch_scc1 .Lna_sl_b_w1s
	ds_read_b128 v[146:149], v199 offset:0
	ds_read_b128 v[150:153], v199 offset:32
	ds_read_b128 v[154:157], v199 offset:64
	ds_read_b128 v[158:161], v199 offset:96
	s_waitcnt lgkmcnt(3)
	v_mfma_f32_32x32x16_bf16 v[34:49], v[146:149], v[98:101], v[114:129]
	s_waitcnt lgkmcnt(2)
	v_mfma_f32_32x32x16_bf16 v[34:49], v[150:153], v[102:105], v[34:49]
	s_waitcnt lgkmcnt(1)
	v_mfma_f32_32x32x16_bf16 v[34:49], v[154:157], v[106:109], v[34:49]
	s_waitcnt lgkmcnt(0)
	v_mfma_f32_32x32x16_bf16 v[34:49], v[158:161], v[110:113], v[34:49]
	v_add_u32_e32 v210, s25, v208
	ds_read_b128 v[146:149], v210 offset:0
	ds_read_b128 v[150:153], v210 offset:32
	ds_read_b128 v[154:157], v210 offset:64
	ds_read_b128 v[158:161], v210 offset:96
	s_waitcnt lgkmcnt(0)
	s_nop 15
	v_add_f32_e32 v34, v34, v146
	v_add_f32_e32 v35, v35, v147
	v_add_f32_e32 v36, v36, v148
	v_add_f32_e32 v37, v37, v149
	v_add_f32_e32 v38, v38, v150
	v_add_f32_e32 v39, v39, v151
	v_add_f32_e32 v40, v40, v152
	v_add_f32_e32 v41, v41, v153
	v_add_f32_e32 v42, v42, v154
	v_add_f32_e32 v43, v43, v155
	v_add_f32_e32 v44, v44, v156
	v_add_f32_e32 v45, v45, v157
	v_add_f32_e32 v46, v46, v158
	v_add_f32_e32 v47, v47, v159
	v_add_f32_e32 v48, v48, v160
	v_add_f32_e32 v49, v49, v161
	v_cndmask_b32_e64 v34, v229, v34, s[48:49]
	v_cndmask_b32_e64 v35, v229, v35, s[48:49]
	v_cndmask_b32_e64 v36, v229, v36, s[48:49]
	v_cndmask_b32_e64 v37, v229, v37, s[48:49]
	v_cndmask_b32_e64 v38, v229, v38, s[48:49]
	v_cndmask_b32_e64 v39, v229, v39, s[48:49]
	v_cndmask_b32_e64 v40, v229, v40, s[48:49]
	v_cndmask_b32_e64 v41, v229, v41, s[48:49]
	v_cndmask_b32_e64 v42, v229, v42, s[48:49]
	v_cndmask_b32_e64 v43, v229, v43, s[48:49]
	v_cndmask_b32_e64 v44, v229, v44, s[48:49]
	v_cndmask_b32_e64 v45, v229, v45, s[48:49]
	v_cndmask_b32_e64 v46, v229, v46, s[48:49]
	v_cndmask_b32_e64 v47, v229, v47, s[48:49]
	v_cndmask_b32_e64 v48, v229, v48, s[48:49]
	v_cndmask_b32_e64 v49, v229, v49, s[48:49]
	v_max3_f32 v216, v34, v35, v36
	v_max3_f32 v217, v42, v43, v44
	v_max3_f32 v216, v216, v37, v38
	v_max3_f32 v217, v217, v45, v46
	v_max3_f32 v216, v216, v39, v40
	v_max3_f32 v217, v217, v47, v48
	v_max_f32_e32 v216, v216, v41
	v_max_f32_e32 v217, v217, v49
	v_cmp_lt_f32_e32 vcc, 4.0, v216
	v_cmp_lt_f32_e64 s[28:29], 4.0, v217
	s_or_b64 s[28:29], s[28:29], vcc
	s_or_b64 s[28:29], s[28:29], s[26:27]
	s_cmp_lg_u64 s[28:29], 0
	s_cbranch_scc0 .Lna_nr_w1s
	v_max_f32_e32 v216, v216, v217
	v_mov_b32_e32 v217, v216
	s_nop 1
	v_permlane32_swap_b32_e32 v216, v217
	v_max_f32_e32 v215, v216, v217
	s_nop 15
	v_max_f32_e32 v216, v215, v220
	v_cmp_lt_f32_e32 vcc, 0xf0c9f2ca, v215
	s_nop 1
	v_cndmask_b32_e32 v216, 0, v216, vcc
	v_exp_f32_e64 v217, -v216
	v_add_f32_e32 v212, v212, v216
	v_and_b32_e32 v217, v217, v221
	v_sub_f32_e32 v34, v34, v216
	v_sub_f32_e32 v35, v35, v216
	v_sub_f32_e32 v36, v36, v216
	v_sub_f32_e32 v37, v37, v216
	v_sub_f32_e32 v38, v38, v216
	v_sub_f32_e32 v39, v39, v216
	v_sub_f32_e32 v40, v40, v216
	v_sub_f32_e32 v41, v41, v216
	v_sub_f32_e32 v42, v42, v216
	v_sub_f32_e32 v43, v43, v216
	v_sub_f32_e32 v44, v44, v216
	v_sub_f32_e32 v45, v45, v216
	v_sub_f32_e32 v46, v46, v216
	v_sub_f32_e32 v47, v47, v216
	v_sub_f32_e32 v48, v48, v216
	v_sub_f32_e32 v49, v49, v216
	v_sub_f32_e32 v114, v114, v216
	v_sub_f32_e32 v115, v115, v216
	v_sub_f32_e32 v116, v116, v216
	v_sub_f32_e32 v117, v117, v216
	v_sub_f32_e32 v118, v118, v216
	v_sub_f32_e32 v119, v119, v216
	v_sub_f32_e32 v120, v120, v216
	v_sub_f32_e32 v121, v121, v216
	v_sub_f32_e32 v122, v122, v216
	v_sub_f32_e32 v123, v123, v216
	v_sub_f32_e32 v124, v124, v216
	v_sub_f32_e32 v125, v125, v216
	v_sub_f32_e32 v126, v126, v216
	v_sub_f32_e32 v127, v127, v216
	v_sub_f32_e32 v128, v128, v216
	v_sub_f32_e32 v129, v129, v216
	v_mul_f32_e32 v213, v213, v217
	v_mul_f32_e32 v214, v214, v217
	v_mul_f32_e32 v2, v2, v217
	v_mul_f32_e32 v3, v3, v217
	v_mul_f32_e32 v4, v4, v217
	v_mul_f32_e32 v5, v5, v217
	v_mul_f32_e32 v6, v6, v217
	v_mul_f32_e32 v7, v7, v217
	v_mul_f32_e32 v8, v8, v217
	v_mul_f32_e32 v9, v9, v217
	v_mul_f32_e32 v10, v10, v217
	v_mul_f32_e32 v11, v11, v217
	v_mul_f32_e32 v12, v12, v217
	v_mul_f32_e32 v13, v13, v217
	v_mul_f32_e32 v14, v14, v217
	v_mul_f32_e32 v15, v15, v217
	v_mul_f32_e32 v16, v16, v217
	v_mul_f32_e32 v17, v17, v217
	v_mul_f32_e32 v18, v18, v217
	v_mul_f32_e32 v19, v19, v217
	v_mul_f32_e32 v20, v20, v217
	v_mul_f32_e32 v21, v21, v217
	v_mul_f32_e32 v22, v22, v217
	v_mul_f32_e32 v23, v23, v217
	v_mul_f32_e32 v24, v24, v217
	v_mul_f32_e32 v25, v25, v217
	v_mul_f32_e32 v26, v26, v217
	v_mul_f32_e32 v27, v27, v217
	v_mul_f32_e32 v28, v28, v217
	v_mul_f32_e32 v29, v29, v217
	v_mul_f32_e32 v30, v30, v217
	v_mul_f32_e32 v31, v31, v217
	v_mul_f32_e32 v32, v32, v217
	v_mul_f32_e32 v33, v33, v217
	v_cndmask_b32_e32 v220, v220, v228, vcc
	v_cndmask_b32_e64 v221, v221, -1, vcc
	s_andn2_b64 s[26:27], s[26:27], vcc

.Lna_done_w1:
	s_add_i32 s24, s24, 1
	s_add_i32 s25, s25, 0x150
	s_sub_i32 s36, s24, s23
	s_cmp_lt_u32 s36, s63
	s_cselect_b64 s[40:41], -1, 0
	s_add_i32 s36, s36, 1
	s_cmp_lt_u32 s36, 8
	s_cselect_b64 s[44:45], -1, 0
	s_sub_i32 s37, s36, s62
	s_cmp_lt_u32 s37, 8
	s_cselect_b64 s[46:47], -1, 0
	s_and_b64 s[48:49], s[44:45], s[64:65]
	s_andn2_b64 s[38:39], s[46:47], s[64:65]
	s_or_b64 s[48:49], s[48:49], s[38:39]
	s_or_b64 s[42:43], s[44:45], s[46:47]
	s_and_b64 s[44:45], s[44:45], s[46:47]
	s_and_b64 s[44:45], s[44:45], s[40:41]
	s_cmp_eq_u64 s[44:45], 0
	s_cbranch_scc1 .Lna_slow_w0
	ds_read_b128 v[146:149], v199 offset:9216
	ds_read_b128 v[150:153], v199 offset:9248
	ds_read_b128 v[154:157], v199 offset:9280
	ds_read_b128 v[158:161], v199 offset:9312
	v_add_u32_e32 v210, s25, v208
	v_exp_f32_e32 v34, v34
	v_exp_f32_e32 v35, v35
	v_exp_f32_e32 v36, v36
	v_exp_f32_e32 v37, v37
	v_add_f32_e32 v213, v213, v34
	v_add_f32_e32 v214, v214, v35
	s_waitcnt lgkmcnt(3)
	v_mfma_f32_32x32x16_bf16 v[66:81], v[146:149], v[98:101], v[114:129]
	ds_read_b64 v[162:163], v201 offset:0
	ds_read_b64 v[164:165], v201 offset:16
	v_add_f32_e32 v213, v213, v36
	v_add_f32_e32 v214, v214, v37
	v_exp_f32_e32 v38, v38
	v_exp_f32_e32 v39, v39
	v_exp_f32_e32 v40, v40
	v_exp_f32_e32 v41, v41
	s_waitcnt lgkmcnt(4)
	v_mfma_f32_32x32x16_bf16 v[66:81], v[150:153], v[102:105], v[66:81]
	ds_read_b64 v[166:167], v201 offset:4352
	ds_read_b64 v[168:169], v201 offset:4368
	v_add_f32_e32 v213, v213, v38
	v_add_f32_e32 v214, v214, v39
	v_add_f32_e32 v213, v213, v40
	v_add_f32_e32 v214, v214, v41
	v_cvt_pk_bf16_f32 v34, v34, v35
	v_cvt_pk_bf16_f32 v35, v36, v37
	v_cvt_pk_bf16_f32 v36, v38, v39
	v_cvt_pk_bf16_f32 v37, v40, v41
	s_waitcnt lgkmcnt(5)
	v_mfma_f32_32x32x16_bf16 v[66:81], v[154:157], v[106:109], v[66:81]
	ds_read_b64 v[170:171], v201 offset:32
	ds_read_b64 v[172:173], v201 offset:48
	v_exp_f32_e32 v42, v42
	v_exp_f32_e32 v43, v43
	v_exp_f32_e32 v44, v44
	v_exp_f32_e32 v45, v45
	v_add_f32_e32 v213, v213, v42
	s_waitcnt lgkmcnt(6)
	v_mfma_f32_32x32x16_bf16 v[66:81], v[158:161], v[110:113], v[66:81]
	ds_read_b64 v[174:175], v201 offset:4384
	ds_read_b64 v[176:177], v201 offset:4400
	ds_read_b128 v[146:149], v210 offset:0
	ds_read_b128 v[150:153], v210 offset:32
	ds_read_b128 v[154:157], v210 offset:64
	ds_read_b128 v[158:161], v210 offset:96
	v_add_f32_e32 v214, v214, v43
	v_add_f32_e32 v213, v213, v44
	v_add_f32_e32 v214, v214, v45
	v_exp_f32_e32 v46, v46
	v_exp_f32_e32 v47, v47
	v_exp_f32_e32 v48, v48
	s_waitcnt lgkmcnt(10)
	v_mfma_f32_32x32x16_bf16 v[2:17], v[162:165], v[34:37], v[2:17]
	v_exp_f32_e32 v49, v49
	v_add_f32_e32 v213, v213, v46
	v_add_f32_e32 v214, v214, v47
	v_add_f32_e32 v213, v213, v48
	v_add_f32_e32 v214, v214, v49
	v_cvt_pk_bf16_f32 v42, v42, v43
	v_cvt_pk_bf16_f32 v43, v44, v45
	v_cvt_pk_bf16_f32 v44, v46, v47
	s_waitcnt lgkmcnt(8)
	v_mfma_f32_32x32x16_bf16 v[18:33], v[166:169], v[34:37], v[18:33]
	v_cvt_pk_bf16_f32 v45, v48, v49
	s_waitcnt lgkmcnt(0)
	v_add_f32_e32 v66, v66, v146
	v_add_f32_e32 v67, v67, v147
	v_add_f32_e32 v68, v68, v148
	v_add_f32_e32 v69, v69, v149
	v_add_f32_e32 v70, v70, v150
	v_add_f32_e32 v71, v71, v151
	v_add_f32_e32 v72, v72, v152
	v_add_f32_e32 v73, v73, v153
	v_mfma_f32_32x32x16_bf16 v[2:17], v[170:173], v[42:45], v[2:17]
	v_add_f32_e32 v74, v74, v154
	v_add_f32_e32 v75, v75, v155
	v_add_f32_e32 v76, v76, v156
	v_add_f32_e32 v77, v77, v157
	v_add_f32_e32 v78, v78, v158
	v_add_f32_e32 v79, v79, v159
	v_add_f32_e32 v80, v80, v160
	v_add_f32_e32 v81, v81, v161
	v_max3_f32 v216, v66, v67, v68
	v_mfma_f32_32x32x16_bf16 v[18:33], v[174:177], v[42:45], v[18:33]
	s_waitcnt vmcnt(2)
	ds_write_b128 v204, v[188:191] offset:0
	ds_write_b64 v205, v[192:193] offset:8704
	ds_write_b64 v205, v[194:195] offset:8712
	global_load_dwordx4 v[188:191], v206, s[12:13]
	s_add_i32 s20, s20, 1
	s_add_u32 s12, s12, 0x2000
	s_addc_u32 s13, s13, 0
	s_cmp_eq_u32 s20, s22
	s_cselect_b32 s12, s16, s12
	s_cselect_b32 s13, s17, s13
	global_load_dwordx4 v[192:195], v207, s[14:15]
	s_add_i32 s21, s21, 1
	s_add_u32 s14, s14, 0x80
	s_addc_u32 s15, s15, 0
	s_cmp_eq_u32 s21, s22
	s_cselect_b32 s14, s18, s14
	s_cselect_b32 s15, s19, s15
	v_max3_f32 v217, v74, v75, v76
	v_max3_f32 v216, v216, v69, v70
	v_max3_f32 v217, v217, v77, v78
	v_max3_f32 v216, v216, v71, v72
	v_max3_f32 v217, v217, v79, v80
	v_max_f32_e32 v216, v216, v73
	v_max_f32_e32 v217, v217, v81
	v_cmp_lt_f32_e32 vcc, 4.0, v216
	v_cmp_lt_f32_e64 s[28:29], 4.0, v217
	s_or_b64 s[28:29], s[28:29], vcc
	s_or_b64 s[28:29], s[28:29], s[26:27]
	s_cmp_lg_u64 s[28:29], 0
	s_cbranch_scc0 .Lna_nr_w0f
	v_max_f32_e32 v216, v216, v217
	v_mov_b32_e32 v217, v216
	s_nop 1
	v_permlane32_swap_b32_e32 v216, v217
	v_max_f32_e32 v215, v216, v217
	s_nop 15
	v_max_f32_e32 v216, v215, v220
	v_cmp_lt_f32_e32 vcc, 0xf0c9f2ca, v215
	s_nop 1
	v_cndmask_b32_e32 v216, 0, v216, vcc
	v_exp_f32_e64 v217, -v216
	v_add_f32_e32 v212, v212, v216
	v_and_b32_e32 v217, v217, v221
	v_sub_f32_e32 v66, v66, v216
	v_sub_f32_e32 v67, v67, v216
	v_sub_f32_e32 v68, v68, v216
	v_sub_f32_e32 v69, v69, v216
	v_sub_f32_e32 v70, v70, v216
	v_sub_f32_e32 v71, v71, v216
	v_sub_f32_e32 v72, v72, v216
	v_sub_f32_e32 v73, v73, v216
	v_sub_f32_e32 v74, v74, v216
	v_sub_f32_e32 v75, v75, v216
	v_sub_f32_e32 v76, v76, v216
	v_sub_f32_e32 v77, v77, v216
	v_sub_f32_e32 v78, v78, v216
	v_sub_f32_e32 v79, v79, v216
	v_sub_f32_e32 v80, v80, v216
	v_sub_f32_e32 v81, v81, v216
	v_sub_f32_e32 v114, v114, v216
	v_sub_f32_e32 v115, v115, v216
	v_sub_f32_e32 v116, v116, v216
	v_sub_f32_e32 v117, v117, v216
	v_sub_f32_e32 v118, v118, v216
	v_sub_f32_e32 v119, v119, v216
	v_sub_f32_e32 v120, v120, v216
	v_sub_f32_e32 v121, v121, v216
	v_sub_f32_e32 v122, v122, v216
	v_sub_f32_e32 v123, v123, v216
	v_sub_f32_e32 v124, v124, v216
	v_sub_f32_e32 v125, v125, v216
	v_sub_f32_e32 v126, v126, v216
	v_sub_f32_e32 v127, v127, v216
	v_sub_f32_e32 v128, v128, v216
	v_sub_f32_e32 v129, v129, v216
	v_mul_f32_e32 v213, v213, v217
	v_mul_f32_e32 v214, v214, v217
	v_mul_f32_e32 v2, v2, v217
	v_mul_f32_e32 v3, v3, v217
	v_mul_f32_e32 v4, v4, v217
	v_mul_f32_e32 v5, v5, v217
	v_mul_f32_e32 v6, v6, v217
	v_mul_f32_e32 v7, v7, v217
	v_mul_f32_e32 v8, v8, v217
	v_mul_f32_e32 v9, v9, v217
	v_mul_f32_e32 v10, v10, v217
	v_mul_f32_e32 v11, v11, v217
	v_mul_f32_e32 v12, v12, v217
	v_mul_f32_e32 v13, v13, v217
	v_mul_f32_e32 v14, v14, v217
	v_mul_f32_e32 v15, v15, v217
	v_mul_f32_e32 v16, v16, v217
	v_mul_f32_e32 v17, v17, v217
	v_mul_f32_e32 v18, v18, v217
	v_mul_f32_e32 v19, v19, v217
	v_mul_f32_e32 v20, v20, v217
	v_mul_f32_e32 v21, v21, v217
	v_mul_f32_e32 v22, v22, v217
	v_mul_f32_e32 v23, v23, v217
	v_mul_f32_e32 v24, v24, v217
	v_mul_f32_e32 v25, v25, v217
	v_mul_f32_e32 v26, v26, v217
	v_mul_f32_e32 v27, v27, v217
	v_mul_f32_e32 v28, v28, v217
	v_mul_f32_e32 v29, v29, v217
	v_mul_f32_e32 v30, v30, v217
	v_mul_f32_e32 v31, v31, v217
	v_mul_f32_e32 v32, v32, v217
	v_mul_f32_e32 v33, v33, v217
	v_cndmask_b32_e32 v220, v220, v228, vcc
	v_cndmask_b32_e64 v221, v221, -1, vcc
	s_andn2_b64 s[26:27], s[26:27], vcc

.Lna_sl_a_w0s:
	s_waitcnt lgkmcnt(0)
	s_cmp_eq_u64 s[42:43], 0
	s_cbranch_scc1 .Lna_sl_b_w0s
	ds_read_b128 v[146:149], v199 offset:9216
	ds_read_b128 v[150:153], v199 offset:9248
	ds_read_b128 v[154:157], v199 offset:9280
	ds_read_b128 v[158:161], v199 offset:9312
	s_waitcnt lgkmcnt(3)
	v_mfma_f32_32x32x16_bf16 v[66:81], v[146:149], v[98:101], v[114:129]
	s_waitcnt lgkmcnt(2)
	v_mfma_f32_32x32x16_bf16 v[66:81], v[150:153], v[102:105], v[66:81]
	s_waitcnt lgkmcnt(1)
	v_mfma_f32_32x32x16_bf16 v[66:81], v[154:157], v[106:109], v[66:81]
	s_waitcnt lgkmcnt(0)
	v_mfma_f32_32x32x16_bf16 v[66:81], v[158:161], v[110:113], v[66:81]
	v_add_u32_e32 v210, s25, v208
	ds_read_b128 v[146:149], v210 offset:0
	ds_read_b128 v[150:153], v210 offset:32
	ds_read_b128 v[154:157], v210 offset:64
	ds_read_b128 v[158:161], v210 offset:96
	s_waitcnt lgkmcnt(0)
	s_nop 15
	v_add_f32_e32 v66, v66, v146
	v_add_f32_e32 v67, v67, v147
	v_add_f32_e32 v68, v68, v148
	v_add_f32_e32 v69, v69, v149
	v_add_f32_e32 v70, v70, v150
	v_add_f32_e32 v71, v71, v151
	v_add_f32_e32 v72, v72, v152
	v_add_f32_e32 v73, v73, v153
	v_add_f32_e32 v74, v74, v154
	v_add_f32_e32 v75, v75, v155
	v_add_f32_e32 v76, v76, v156
	v_add_f32_e32 v77, v77, v157
	v_add_f32_e32 v78, v78, v158
	v_add_f32_e32 v79, v79, v159
	v_add_f32_e32 v80, v80, v160
	v_add_f32_e32 v81, v81, v161
	v_cndmask_b32_e64 v66, v229, v66, s[48:49]
	v_cndmask_b32_e64 v67, v229, v67, s[48:49]
	v_cndmask_b32_e64 v68, v229, v68, s[48:49]
	v_cndmask_b32_e64 v69, v229, v69, s[48:49]
	v_cndmask_b32_e64 v70, v229, v70, s[48:49]
	v_cndmask_b32_e64 v71, v229, v71, s[48:49]
	v_cndmask_b32_e64 v72, v229, v72, s[48:49]
	v_cndmask_b32_e64 v73, v229, v73, s[48:49]
	v_cndmask_b32_e64 v74, v229, v74, s[48:49]
	v_cndmask_b32_e64 v75, v229, v75, s[48:49]
	v_cndmask_b32_e64 v76, v229, v76, s[48:49]
	v_cndmask_b32_e64 v77, v229, v77, s[48:49]
	v_cndmask_b32_e64 v78, v229, v78, s[48:49]
	v_cndmask_b32_e64 v79, v229, v79, s[48:49]
	v_cndmask_b32_e64 v80, v229, v80, s[48:49]
	v_cndmask_b32_e64 v81, v229, v81, s[48:49]
	v_max3_f32 v216, v66, v67, v68
	v_max3_f32 v217, v74, v75, v76
	v_max3_f32 v216, v216, v69, v70
	v_max3_f32 v217, v217, v77, v78
	v_max3_f32 v216, v216, v71, v72
	v_max3_f32 v217, v217, v79, v80
	v_max_f32_e32 v216, v216, v73
	v_max_f32_e32 v217, v217, v81
	v_cmp_lt_f32_e32 vcc, 4.0, v216
	v_cmp_lt_f32_e64 s[28:29], 4.0, v217
	s_or_b64 s[28:29], s[28:29], vcc
	s_or_b64 s[28:29], s[28:29], s[26:27]
	s_cmp_lg_u64 s[28:29], 0
	s_cbranch_scc0 .Lna_nr_w0s
	v_max_f32_e32 v216, v216, v217
	v_mov_b32_e32 v217, v216
	s_nop 1
	v_permlane32_swap_b32_e32 v216, v217
	v_max_f32_e32 v215, v216, v217
	s_nop 15
	v_max_f32_e32 v216, v215, v220
	v_cmp_lt_f32_e32 vcc, 0xf0c9f2ca, v215
	s_nop 1
	v_cndmask_b32_e32 v216, 0, v216, vcc
	v_exp_f32_e64 v217, -v216
	v_add_f32_e32 v212, v212, v216
	v_and_b32_e32 v217, v217, v221
	v_sub_f32_e32 v66, v66, v216
	v_sub_f32_e32 v67, v67, v216
	v_sub_f32_e32 v68, v68, v216
	v_sub_f32_e32 v69, v69, v216
	v_sub_f32_e32 v70, v70, v216
	v_sub_f32_e32 v71, v71, v216
	v_sub_f32_e32 v72, v72, v216
	v_sub_f32_e32 v73, v73, v216
	v_sub_f32_e32 v74, v74, v216
	v_sub_f32_e32 v75, v75, v216
	v_sub_f32_e32 v76, v76, v216
	v_sub_f32_e32 v77, v77, v216
	v_sub_f32_e32 v78, v78, v216
	v_sub_f32_e32 v79, v79, v216
	v_sub_f32_e32 v80, v80, v216
	v_sub_f32_e32 v81, v81, v216
	v_sub_f32_e32 v114, v114, v216
	v_sub_f32_e32 v115, v115, v216
	v_sub_f32_e32 v116, v116, v216
	v_sub_f32_e32 v117, v117, v216
	v_sub_f32_e32 v118, v118, v216
	v_sub_f32_e32 v119, v119, v216
	v_sub_f32_e32 v120, v120, v216
	v_sub_f32_e32 v121, v121, v216
	v_sub_f32_e32 v122, v122, v216
	v_sub_f32_e32 v123, v123, v216
	v_sub_f32_e32 v124, v124, v216
	v_sub_f32_e32 v125, v125, v216
	v_sub_f32_e32 v126, v126, v216
	v_sub_f32_e32 v127, v127, v216
	v_sub_f32_e32 v128, v128, v216
	v_sub_f32_e32 v129, v129, v216
	v_mul_f32_e32 v213, v213, v217
	v_mul_f32_e32 v214, v214, v217
	v_mul_f32_e32 v2, v2, v217
	v_mul_f32_e32 v3, v3, v217
	v_mul_f32_e32 v4, v4, v217
	v_mul_f32_e32 v5, v5, v217
	v_mul_f32_e32 v6, v6, v217
	v_mul_f32_e32 v7, v7, v217
	v_mul_f32_e32 v8, v8, v217
	v_mul_f32_e32 v9, v9, v217
	v_mul_f32_e32 v10, v10, v217
	v_mul_f32_e32 v11, v11, v217
	v_mul_f32_e32 v12, v12, v217
	v_mul_f32_e32 v13, v13, v217
	v_mul_f32_e32 v14, v14, v217
	v_mul_f32_e32 v15, v15, v217
	v_mul_f32_e32 v16, v16, v217
	v_mul_f32_e32 v17, v17, v217
	v_mul_f32_e32 v18, v18, v217
	v_mul_f32_e32 v19, v19, v217
	v_mul_f32_e32 v20, v20, v217
	v_mul_f32_e32 v21, v21, v217
	v_mul_f32_e32 v22, v22, v217
	v_mul_f32_e32 v23, v23, v217
	v_mul_f32_e32 v24, v24, v217
	v_mul_f32_e32 v25, v25, v217
	v_mul_f32_e32 v26, v26, v217
	v_mul_f32_e32 v27, v27, v217
	v_mul_f32_e32 v28, v28, v217
	v_mul_f32_e32 v29, v29, v217
	v_mul_f32_e32 v30, v30, v217
	v_mul_f32_e32 v31, v31, v217
	v_mul_f32_e32 v32, v32, v217
	v_mul_f32_e32 v33, v33, v217
	v_cndmask_b32_e32 v220, v220, v228, vcc
	v_cndmask_b32_e64 v221, v221, -1, vcc
	s_andn2_b64 s[26:27], s[26:27], vcc

.Lna_done_w0:
	s_add_i32 s24, s24, 1
	s_add_i32 s25, s25, 0x150
	s_add_i32 s33, s33, -1
	s_cmp_lg_u32 s33, 0
	s_cbranch_scc1 .Lna_wloop
	v_sub_f32_e32 v114, 0, v212
	v_mov_b32_e32 v115, v114
	v_mov_b32_e32 v116, v114
	v_mov_b32_e32 v117, v114
	v_mov_b32_e32 v118, v114
	v_mov_b32_e32 v119, v114
	v_mov_b32_e32 v120, v114
	v_mov_b32_e32 v121, v114
	v_mov_b32_e32 v122, v114
	v_mov_b32_e32 v123, v114
	v_mov_b32_e32 v124, v114
	v_mov_b32_e32 v125, v114
	v_mov_b32_e32 v126, v114
	v_mov_b32_e32 v127, v114
	v_mov_b32_e32 v128, v114
	v_mov_b32_e32 v129, v114
	v_mov_b32_e32 v130, v114
	v_mov_b32_e32 v131, v114
	v_mov_b32_e32 v132, v114
	v_mov_b32_e32 v133, v114
	v_mov_b32_e32 v134, v114
	v_mov_b32_e32 v135, v114
	v_mov_b32_e32 v136, v114
	v_mov_b32_e32 v137, v114
	v_mov_b32_e32 v138, v114
	v_mov_b32_e32 v139, v114
	v_mov_b32_e32 v140, v114
	v_mov_b32_e32 v141, v114
	v_mov_b32_e32 v142, v114
	v_mov_b32_e32 v143, v114
	v_mov_b32_e32 v144, v114
	v_mov_b32_e32 v145, v114
	s_sub_i32 s36, s24, s23
	s_cmp_lt_u32 s36, s63
	s_cselect_b64 s[40:41], -1, 0
	s_mov_b64 s[42:43], -1
	s_cmp_eq_u64 s[40:41], 0
	s_cbranch_scc1 .Lna_slow_wc
	ds_read_b128 v[146:149], v200 offset:0
	ds_read_b128 v[150:153], v200 offset:4608
	ds_read_b128 v[154:157], v200 offset:32
	ds_read_b128 v[158:161], v200 offset:4640
	v_exp_f32_e32 v66, v66
	v_exp_f32_e32 v67, v67
	v_exp_f32_e32 v68, v68
	s_waitcnt lgkmcnt(2)
	v_mfma_f32_32x32x16_bf16 v[34:49], v[146:149], v[98:101], v[114:129]
	ds_read_b128 v[146:149], v200 offset:64
	v_exp_f32_e32 v69, v69
	v_add_f32_e32 v213, v213, v66
	v_add_f32_e32 v214, v214, v67
	v_add_f32_e32 v213, v213, v68
	v_add_f32_e32 v214, v214, v69
	v_mfma_f32_32x32x16_bf16 v[50:65], v[150:153], v[98:101], v[130:145]
	ds_read_b128 v[150:153], v200 offset:4672
	v_exp_f32_e32 v70, v70
	v_exp_f32_e32 v71, v71
	v_exp_f32_e32 v72, v72
	s_waitcnt lgkmcnt(2)
	v_mfma_f32_32x32x16_bf16 v[34:49], v[154:157], v[102:105], v[34:49]
	ds_read_b128 v[154:157], v200 offset:96
	v_exp_f32_e32 v73, v73
	v_add_f32_e32 v213, v213, v70
	v_add_f32_e32 v214, v214, v71
	v_add_f32_e32 v213, v213, v72
	v_mfma_f32_32x32x16_bf16 v[50:65], v[158:161], v[102:105], v[50:65]
	ds_read_b128 v[158:161], v200 offset:4704
	v_add_f32_e32 v214, v214, v73
	v_cvt_pk_bf16_f32 v66, v66, v67
	v_cvt_pk_bf16_f32 v67, v68, v69
	v_cvt_pk_bf16_f32 v68, v70, v71
	v_cvt_pk_bf16_f32 v69, v72, v73
	v_exp_f32_e32 v74, v74
	s_waitcnt lgkmcnt(2)
	v_mfma_f32_32x32x16_bf16 v[34:49], v[146:149], v[106:109], v[34:49]
	ds_read_b64 v[162:163], v201 offset:8704
	ds_read_b64 v[164:165], v201 offset:8720
	v_exp_f32_e32 v75, v75
	v_exp_f32_e32 v76, v76
	v_exp_f32_e32 v77, v77
	v_mfma_f32_32x32x16_bf16 v[50:65], v[150:153], v[106:109], v[50:65]
	ds_read_b64 v[166:167], v201 offset:13056
	ds_read_b64 v[168:169], v201 offset:13072
	v_add_f32_e32 v213, v213, v74
	v_add_f32_e32 v214, v214, v75
	v_add_f32_e32 v213, v213, v76
	v_add_f32_e32 v214, v214, v77
	s_waitcnt lgkmcnt(4)
	v_mfma_f32_32x32x16_bf16 v[34:49], v[154:157], v[110:113], v[34:49]
	ds_read_b64 v[170:171], v201 offset:8736
	ds_read_b64 v[172:173], v201 offset:8752
	v_exp_f32_e32 v78, v78
	v_exp_f32_e32 v79, v79
	v_exp_f32_e32 v80, v80
	v_mfma_f32_32x32x16_bf16 v[50:65], v[158:161], v[110:113], v[50:65]
	ds_read_b64 v[174:175], v201 offset:13088
	ds_read_b64 v[176:177], v201 offset:13104
	v_exp_f32_e32 v81, v81
	v_add_f32_e32 v213, v213, v78
	v_add_f32_e32 v214, v214, v79
	v_add_f32_e32 v213, v213, v80
	v_add_f32_e32 v214, v214, v81
	s_waitcnt lgkmcnt(6)
	v_mfma_f32_32x32x16_bf16 v[2:17], v[162:165], v[66:69], v[2:17]
	v_cvt_pk_bf16_f32 v74, v74, v75
	v_cvt_pk_bf16_f32 v75, v76, v77
	v_cvt_pk_bf16_f32 v76, v78, v79
	v_cvt_pk_bf16_f32 v77, v80, v81
	s_waitcnt lgkmcnt(4)
	v_mfma_f32_32x32x16_bf16 v[18:33], v[166:169], v[66:69], v[18:33]
	v_max3_f32 v216, v34, v35, v36
	v_max3_f32 v217, v50, v51, v52
	v_max3_f32 v216, v216, v37, v38
	v_max3_f32 v217, v217, v53, v54
	v_max3_f32 v216, v216, v39, v40
	v_max3_f32 v217, v217, v55, v56
	v_max3_f32 v216, v216, v41, v42
	s_waitcnt lgkmcnt(2)
	v_mfma_f32_32x32x16_bf16 v[2:17], v[170:173], v[74:77], v[2:17]
	v_max3_f32 v217, v217, v57, v58
	v_max3_f32 v216, v216, v43, v44
	v_max3_f32 v217, v217, v59, v60
	v_max3_f32 v216, v216, v45, v46
	v_max3_f32 v217, v217, v61, v62
	v_max3_f32 v216, v216, v47, v48
	s_waitcnt lgkmcnt(0)
	v_mfma_f32_32x32x16_bf16 v[18:33], v[174:177], v[74:77], v[18:33]
	s_waitcnt vmcnt(2)
	ds_write_b128 v204, v[230:233] offset:9216
	ds_write_b64 v205, v[234:235] offset:0
	ds_write_b64 v205, v[236:237] offset:8
	global_load_dwordx4 v[230:233], v206, s[12:13]
	s_add_u32 s12, s12, 0x2000
	s_addc_u32 s13, s13, 0
	global_load_dwordx4 v[234:237], v207, s[14:15]
	s_add_u32 s14, s14, 0x80
	s_addc_u32 s15, s15, 0
	v_max3_f32 v217, v217, v63, v64
	v_max_f32_e32 v216, v216, v49
	v_max_f32_e32 v217, v217, v65
	v_cmp_lt_f32_e32 vcc, 4.0, v216
	v_cmp_lt_f32_e64 s[28:29], 4.0, v217
	s_or_b64 vcc, vcc, s[28:29]
	s_cbranch_vccz .Lna_nr_wcf
	v_max_f32_e32 v216, v216, v217
	v_mov_b32_e32 v217, v216
	s_nop 1
	v_permlane32_swap_b32_e32 v216, v217
	v_max_f32_e32 v215, v216, v217
	s_nop 15
	v_max_f32_e32 v216, v215, v220
	v_exp_f32_e64 v217, -v216
	v_add_f32_e32 v212, v212, v216
	v_and_b32_e32 v217, v217, v221
	v_sub_f32_e32 v34, v34, v216
	v_sub_f32_e32 v35, v35, v216
	v_sub_f32_e32 v36, v36, v216
	v_sub_f32_e32 v37, v37, v216
	v_sub_f32_e32 v38, v38, v216
	v_sub_f32_e32 v39, v39, v216
	v_sub_f32_e32 v40, v40, v216
	v_sub_f32_e32 v41, v41, v216
	v_sub_f32_e32 v42, v42, v216
	v_sub_f32_e32 v43, v43, v216
	v_sub_f32_e32 v44, v44, v216
	v_sub_f32_e32 v45, v45, v216
	v_sub_f32_e32 v46, v46, v216
	v_sub_f32_e32 v47, v47, v216
	v_sub_f32_e32 v48, v48, v216
	v_sub_f32_e32 v49, v49, v216
	v_sub_f32_e32 v50, v50, v216
	v_sub_f32_e32 v51, v51, v216
	v_sub_f32_e32 v52, v52, v216
	v_sub_f32_e32 v53, v53, v216
	v_sub_f32_e32 v54, v54, v216
	v_sub_f32_e32 v55, v55, v216
	v_sub_f32_e32 v56, v56, v216
	v_sub_f32_e32 v57, v57, v216
	v_sub_f32_e32 v58, v58, v216
	v_sub_f32_e32 v59, v59, v216
	v_sub_f32_e32 v60, v60, v216
	v_sub_f32_e32 v61, v61, v216
	v_sub_f32_e32 v62, v62, v216
	v_sub_f32_e32 v63, v63, v216
	v_sub_f32_e32 v64, v64, v216
	v_sub_f32_e32 v65, v65, v216
	v_sub_f32_e32 v114, v114, v216
	v_sub_f32_e32 v115, v115, v216
	v_sub_f32_e32 v116, v116, v216
	v_sub_f32_e32 v117, v117, v216
	v_sub_f32_e32 v118, v118, v216
	v_sub_f32_e32 v119, v119, v216
	v_sub_f32_e32 v120, v120, v216
	v_sub_f32_e32 v121, v121, v216
	v_sub_f32_e32 v122, v122, v216
	v_sub_f32_e32 v123, v123, v216
	v_sub_f32_e32 v124, v124, v216
	v_sub_f32_e32 v125, v125, v216
	v_sub_f32_e32 v126, v126, v216
	v_sub_f32_e32 v127, v127, v216
	v_sub_f32_e32 v128, v128, v216
	v_sub_f32_e32 v129, v129, v216
	v_sub_f32_e32 v130, v130, v216
	v_sub_f32_e32 v131, v131, v216
	v_sub_f32_e32 v132, v132, v216
	v_sub_f32_e32 v133, v133, v216
	v_sub_f32_e32 v134, v134, v216
	v_sub_f32_e32 v135, v135, v216
	v_sub_f32_e32 v136, v136, v216
	v_sub_f32_e32 v137, v137, v216
	v_sub_f32_e32 v138, v138, v216
	v_sub_f32_e32 v139, v139, v216
	v_sub_f32_e32 v140, v140, v216
	v_sub_f32_e32 v141, v141, v216
	v_sub_f32_e32 v142, v142, v216
	v_sub_f32_e32 v143, v143, v216
	v_sub_f32_e32 v144, v144, v216
	v_sub_f32_e32 v145, v145, v216
	v_mul_f32_e32 v213, v213, v217
	v_mul_f32_e32 v214, v214, v217
	v_mul_f32_e32 v2, v2, v217
	v_mul_f32_e32 v3, v3, v217
	v_mul_f32_e32 v4, v4, v217
	v_mul_f32_e32 v5, v5, v217
	v_mul_f32_e32 v6, v6, v217
	v_mul_f32_e32 v7, v7, v217
	v_mul_f32_e32 v8, v8, v217
	v_mul_f32_e32 v9, v9, v217
	v_mul_f32_e32 v10, v10, v217
	v_mul_f32_e32 v11, v11, v217
	v_mul_f32_e32 v12, v12, v217
	v_mul_f32_e32 v13, v13, v217
	v_mul_f32_e32 v14, v14, v217
	v_mul_f32_e32 v15, v15, v217
	v_mul_f32_e32 v16, v16, v217
	v_mul_f32_e32 v17, v17, v217
	v_mul_f32_e32 v18, v18, v217
	v_mul_f32_e32 v19, v19, v217
	v_mul_f32_e32 v20, v20, v217
	v_mul_f32_e32 v21, v21, v217
	v_mul_f32_e32 v22, v22, v217
	v_mul_f32_e32 v23, v23, v217
	v_mul_f32_e32 v24, v24, v217
	v_mul_f32_e32 v25, v25, v217
	v_mul_f32_e32 v26, v26, v217
	v_mul_f32_e32 v27, v27, v217
	v_mul_f32_e32 v28, v28, v217
	v_mul_f32_e32 v29, v29, v217
	v_mul_f32_e32 v30, v30, v217
	v_mul_f32_e32 v31, v31, v217
	v_mul_f32_e32 v32, v32, v217
	v_mul_f32_e32 v33, v33, v217

.Lna_sl_a_wcs:
	s_waitcnt lgkmcnt(0)
	s_cmp_eq_u64 s[42:43], 0
	s_cbranch_scc1 .Lna_sl_b_wcs
	ds_read_b128 v[146:149], v200 offset:0
	ds_read_b128 v[150:153], v200 offset:4608
	ds_read_b128 v[154:157], v200 offset:32
	ds_read_b128 v[158:161], v200 offset:4640
	ds_read_b128 v[162:165], v200 offset:64
	ds_read_b128 v[166:169], v200 offset:4672
	ds_read_b128 v[170:173], v200 offset:96
	ds_read_b128 v[174:177], v200 offset:4704
	s_waitcnt lgkmcnt(7)
	v_mfma_f32_32x32x16_bf16 v[34:49], v[146:149], v[98:101], v[114:129]
	s_waitcnt lgkmcnt(6)
	v_mfma_f32_32x32x16_bf16 v[50:65], v[150:153], v[98:101], v[130:145]
	s_waitcnt lgkmcnt(5)
	v_mfma_f32_32x32x16_bf16 v[34:49], v[154:157], v[102:105], v[34:49]
	s_waitcnt lgkmcnt(4)
	v_mfma_f32_32x32x16_bf16 v[50:65], v[158:161], v[102:105], v[50:65]
	s_waitcnt lgkmcnt(3)
	v_mfma_f32_32x32x16_bf16 v[34:49], v[162:165], v[106:109], v[34:49]
	s_waitcnt lgkmcnt(2)
	v_mfma_f32_32x32x16_bf16 v[50:65], v[166:169], v[106:109], v[50:65]
	s_waitcnt lgkmcnt(1)
	v_mfma_f32_32x32x16_bf16 v[34:49], v[170:173], v[110:113], v[34:49]
	s_waitcnt lgkmcnt(0)
	v_mfma_f32_32x32x16_bf16 v[50:65], v[174:177], v[110:113], v[50:65]
	s_nop 15
	v_max3_f32 v216, v34, v35, v36
	v_max3_f32 v217, v50, v51, v52
	v_max3_f32 v216, v216, v37, v38
	v_max3_f32 v217, v217, v53, v54
	v_max3_f32 v216, v216, v39, v40
	v_max3_f32 v217, v217, v55, v56
	v_max3_f32 v216, v216, v41, v42
	v_max3_f32 v217, v217, v57, v58
	v_max3_f32 v216, v216, v43, v44
	v_max3_f32 v217, v217, v59, v60
	v_max3_f32 v216, v216, v45, v46
	v_max3_f32 v217, v217, v61, v62
	v_max3_f32 v216, v216, v47, v48
	v_max3_f32 v217, v217, v63, v64
	v_max_f32_e32 v216, v216, v49
	v_max_f32_e32 v217, v217, v65
	v_cmp_lt_f32_e32 vcc, 4.0, v216
	v_cmp_lt_f32_e64 s[28:29], 4.0, v217
	s_or_b64 vcc, vcc, s[28:29]
	s_cbranch_vccz .Lna_nr_wcs
	v_max_f32_e32 v216, v216, v217
	v_mov_b32_e32 v217, v216
	s_nop 1
	v_permlane32_swap_b32_e32 v216, v217
	v_max_f32_e32 v215, v216, v217
	s_nop 15
	v_max_f32_e32 v216, v215, v220
	v_exp_f32_e64 v217, -v216
	v_add_f32_e32 v212, v212, v216
	v_and_b32_e32 v217, v217, v221
	v_sub_f32_e32 v34, v34, v216
	v_sub_f32_e32 v35, v35, v216
	v_sub_f32_e32 v36, v36, v216
	v_sub_f32_e32 v37, v37, v216
	v_sub_f32_e32 v38, v38, v216
	v_sub_f32_e32 v39, v39, v216
	v_sub_f32_e32 v40, v40, v216
	v_sub_f32_e32 v41, v41, v216
	v_sub_f32_e32 v42, v42, v216
	v_sub_f32_e32 v43, v43, v216
	v_sub_f32_e32 v44, v44, v216
	v_sub_f32_e32 v45, v45, v216
	v_sub_f32_e32 v46, v46, v216
	v_sub_f32_e32 v47, v47, v216
	v_sub_f32_e32 v48, v48, v216
	v_sub_f32_e32 v49, v49, v216
	v_sub_f32_e32 v50, v50, v216
	v_sub_f32_e32 v51, v51, v216
	v_sub_f32_e32 v52, v52, v216
	v_sub_f32_e32 v53, v53, v216
	v_sub_f32_e32 v54, v54, v216
	v_sub_f32_e32 v55, v55, v216
	v_sub_f32_e32 v56, v56, v216
	v_sub_f32_e32 v57, v57, v216
	v_sub_f32_e32 v58, v58, v216
	v_sub_f32_e32 v59, v59, v216
	v_sub_f32_e32 v60, v60, v216
	v_sub_f32_e32 v61, v61, v216
	v_sub_f32_e32 v62, v62, v216
	v_sub_f32_e32 v63, v63, v216
	v_sub_f32_e32 v64, v64, v216
	v_sub_f32_e32 v65, v65, v216
	v_sub_f32_e32 v114, v114, v216
	v_sub_f32_e32 v115, v115, v216
	v_sub_f32_e32 v116, v116, v216
	v_sub_f32_e32 v117, v117, v216
	v_sub_f32_e32 v118, v118, v216
	v_sub_f32_e32 v119, v119, v216
	v_sub_f32_e32 v120, v120, v216
	v_sub_f32_e32 v121, v121, v216
	v_sub_f32_e32 v122, v122, v216
	v_sub_f32_e32 v123, v123, v216
	v_sub_f32_e32 v124, v124, v216
	v_sub_f32_e32 v125, v125, v216
	v_sub_f32_e32 v126, v126, v216
	v_sub_f32_e32 v127, v127, v216
	v_sub_f32_e32 v128, v128, v216
	v_sub_f32_e32 v129, v129, v216
	v_sub_f32_e32 v130, v130, v216
	v_sub_f32_e32 v131, v131, v216
	v_sub_f32_e32 v132, v132, v216
	v_sub_f32_e32 v133, v133, v216
	v_sub_f32_e32 v134, v134, v216
	v_sub_f32_e32 v135, v135, v216
	v_sub_f32_e32 v136, v136, v216
	v_sub_f32_e32 v137, v137, v216
	v_sub_f32_e32 v138, v138, v216
	v_sub_f32_e32 v139, v139, v216
	v_sub_f32_e32 v140, v140, v216
	v_sub_f32_e32 v141, v141, v216
	v_sub_f32_e32 v142, v142, v216
	v_sub_f32_e32 v143, v143, v216
	v_sub_f32_e32 v144, v144, v216
	v_sub_f32_e32 v145, v145, v216
	v_mul_f32_e32 v213, v213, v217
	v_mul_f32_e32 v214, v214, v217
	v_mul_f32_e32 v2, v2, v217
	v_mul_f32_e32 v3, v3, v217
	v_mul_f32_e32 v4, v4, v217
	v_mul_f32_e32 v5, v5, v217
	v_mul_f32_e32 v6, v6, v217
	v_mul_f32_e32 v7, v7, v217
	v_mul_f32_e32 v8, v8, v217
	v_mul_f32_e32 v9, v9, v217
	v_mul_f32_e32 v10, v10, v217
	v_mul_f32_e32 v11, v11, v217
	v_mul_f32_e32 v12, v12, v217
	v_mul_f32_e32 v13, v13, v217
	v_mul_f32_e32 v14, v14, v217
	v_mul_f32_e32 v15, v15, v217
	v_mul_f32_e32 v16, v16, v217
	v_mul_f32_e32 v17, v17, v217
	v_mul_f32_e32 v18, v18, v217
	v_mul_f32_e32 v19, v19, v217
	v_mul_f32_e32 v20, v20, v217
	v_mul_f32_e32 v21, v21, v217
	v_mul_f32_e32 v22, v22, v217
	v_mul_f32_e32 v23, v23, v217
	v_mul_f32_e32 v24, v24, v217
	v_mul_f32_e32 v25, v25, v217
	v_mul_f32_e32 v26, v26, v217
	v_mul_f32_e32 v27, v27, v217
	v_mul_f32_e32 v28, v28, v217
	v_mul_f32_e32 v29, v29, v217
	v_mul_f32_e32 v30, v30, v217
	v_mul_f32_e32 v31, v31, v217
	v_mul_f32_e32 v32, v32, v217
	v_mul_f32_e32 v33, v33, v217

.Lna_done_wc:
	ds_read_b128 v[146:149], v200 offset:9216
	ds_read_b128 v[150:153], v200 offset:13824
	ds_read_b128 v[154:157], v200 offset:9248
	ds_read_b128 v[158:161], v200 offset:13856
	v_exp_f32_e32 v34, v34
	v_exp_f32_e32 v35, v35
	v_exp_f32_e32 v36, v36
	v_exp_f32_e32 v37, v37
	s_waitcnt lgkmcnt(2)
	v_mfma_f32_32x32x16_bf16 v[66:81], v[146:149], v[98:101], v[114:129]
	ds_read_b128 v[146:149], v200 offset:9280
	v_add_f32_e32 v213, v213, v34
	v_add_f32_e32 v214, v214, v35
	v_add_f32_e32 v213, v213, v36
	v_add_f32_e32 v214, v214, v37
	v_exp_f32_e32 v38, v38
	v_exp_f32_e32 v39, v39
	v_mfma_f32_32x32x16_bf16 v[82:97], v[150:153], v[98:101], v[130:145]
	ds_read_b128 v[150:153], v200 offset:13888
	v_exp_f32_e32 v40, v40
	v_exp_f32_e32 v41, v41
	v_add_f32_e32 v213, v213, v38
	v_add_f32_e32 v214, v214, v39
	v_add_f32_e32 v213, v213, v40
	s_waitcnt lgkmcnt(2)
	v_mfma_f32_32x32x16_bf16 v[66:81], v[154:157], v[102:105], v[66:81]
	ds_read_b128 v[154:157], v200 offset:9312
	v_add_f32_e32 v214, v214, v41
	v_cvt_pk_bf16_f32 v34, v34, v35
	v_cvt_pk_bf16_f32 v35, v36, v37
	v_cvt_pk_bf16_f32 v36, v38, v39
	v_cvt_pk_bf16_f32 v37, v40, v41
	v_exp_f32_e32 v42, v42
	v_exp_f32_e32 v43, v43
	v_mfma_f32_32x32x16_bf16 v[82:97], v[158:161], v[102:105], v[82:97]
	ds_read_b128 v[158:161], v200 offset:13920
	v_exp_f32_e32 v44, v44
	v_exp_f32_e32 v45, v45
	v_add_f32_e32 v213, v213, v42
	v_add_f32_e32 v214, v214, v43
	v_add_f32_e32 v213, v213, v44
	s_waitcnt lgkmcnt(2)
	v_mfma_f32_32x32x16_bf16 v[66:81], v[146:149], v[106:109], v[66:81]
	ds_read_b64 v[162:163], v202 offset:0
	ds_read_b64 v[164:165], v202 offset:16
	v_add_f32_e32 v214, v214, v45
	v_exp_f32_e32 v46, v46
	v_exp_f32_e32 v47, v47
	v_exp_f32_e32 v48, v48
	v_mfma_f32_32x32x16_bf16 v[82:97], v[150:153], v[106:109], v[82:97]
	ds_read_b64 v[166:167], v202 offset:4352
	ds_read_b64 v[168:169], v202 offset:4368
	v_exp_f32_e32 v49, v49
	v_add_f32_e32 v213, v213, v46
	v_add_f32_e32 v214, v214, v47
	v_add_f32_e32 v213, v213, v48
	v_add_f32_e32 v214, v214, v49
	v_cvt_pk_bf16_f32 v42, v42, v43
	v_cvt_pk_bf16_f32 v43, v44, v45
	s_waitcnt lgkmcnt(4)
	v_mfma_f32_32x32x16_bf16 v[66:81], v[154:157], v[110:113], v[66:81]
	ds_read_b64 v[170:171], v202 offset:32
	ds_read_b64 v[172:173], v202 offset:48
	v_cvt_pk_bf16_f32 v44, v46, v47
	v_cvt_pk_bf16_f32 v45, v48, v49
	v_exp_f32_e32 v50, v50
	v_exp_f32_e32 v51, v51
	v_exp_f32_e32 v52, v52
	v_mfma_f32_32x32x16_bf16 v[82:97], v[158:161], v[110:113], v[82:97]
	ds_read_b64 v[174:175], v202 offset:4384
	ds_read_b64 v[176:177], v202 offset:4400
	v_exp_f32_e32 v53, v53
	v_add_f32_e32 v213, v213, v50
	v_add_f32_e32 v214, v214, v51
	v_add_f32_e32 v213, v213, v52
	v_add_f32_e32 v214, v214, v53
	v_exp_f32_e32 v54, v54
	s_waitcnt lgkmcnt(6)
	v_mfma_f32_32x32x16_bf16 v[2:17], v[162:165], v[34:37], v[2:17]
	ds_read_b64 v[162:163], v202 offset:64
	ds_read_b64 v[164:165], v202 offset:80
	v_exp_f32_e32 v55, v55
	v_exp_f32_e32 v56, v56
	v_exp_f32_e32 v57, v57
	v_add_f32_e32 v213, v213, v54
	s_waitcnt lgkmcnt(6)
	v_mfma_f32_32x32x16_bf16 v[18:33], v[166:169], v[34:37], v[18:33]
	ds_read_b64 v[166:167], v202 offset:4416
	ds_read_b64 v[168:169], v202 offset:4432
	v_add_f32_e32 v214, v214, v55
	v_add_f32_e32 v213, v213, v56
	v_add_f32_e32 v214, v214, v57
	v_cvt_pk_bf16_f32 v50, v50, v51
	v_cvt_pk_bf16_f32 v51, v52, v53
	v_cvt_pk_bf16_f32 v52, v54, v55
	v_cvt_pk_bf16_f32 v53, v56, v57
	v_exp_f32_e32 v58, v58
	s_waitcnt lgkmcnt(6)
	v_mfma_f32_32x32x16_bf16 v[2:17], v[170:173], v[42:45], v[2:17]
	ds_read_b64 v[170:171], v202 offset:96
	ds_read_b64 v[172:173], v202 offset:112
	v_exp_f32_e32 v59, v59
	v_exp_f32_e32 v60, v60
	v_exp_f32_e32 v61, v61
	s_waitcnt lgkmcnt(6)
	v_mfma_f32_32x32x16_bf16 v[18:33], v[174:177], v[42:45], v[18:33]
	ds_read_b64 v[174:175], v202 offset:4448
	ds_read_b64 v[176:177], v202 offset:4464
	s_waitcnt vmcnt(2)
	ds_write_b128 v204, v[188:191] offset:0
	ds_write_b64 v205, v[192:193] offset:8704
	ds_write_b64 v205, v[194:195] offset:8712
	global_load_dwordx4 v[192:195], v207, s[14:15]
	s_add_u32 s14, s14, 0x80
	s_addc_u32 s15, s15, 0
	v_add_f32_e32 v213, v213, v58
	v_add_f32_e32 v214, v214, v59
	v_add_f32_e32 v213, v213, v60
	v_add_f32_e32 v214, v214, v61
	v_exp_f32_e32 v62, v62
	v_exp_f32_e32 v63, v63
	s_waitcnt lgkmcnt(9)
	v_mfma_f32_32x32x16_bf16 v[2:17], v[162:165], v[50:53], v[2:17]
	v_exp_f32_e32 v64, v64
	v_exp_f32_e32 v65, v65
	v_add_f32_e32 v213, v213, v62
	v_add_f32_e32 v214, v214, v63
	v_add_f32_e32 v213, v213, v64
	v_add_f32_e32 v214, v214, v65
	s_waitcnt lgkmcnt(7)
	v_mfma_f32_32x32x16_bf16 v[18:33], v[166:169], v[50:53], v[18:33]
	v_cvt_pk_bf16_f32 v58, v58, v59
	v_cvt_pk_bf16_f32 v59, v60, v61
	v_cvt_pk_bf16_f32 v60, v62, v63
	v_cvt_pk_bf16_f32 v61, v64, v65
	v_max3_f32 v216, v66, v67, v68
	v_max3_f32 v217, v82, v83, v84
	v_max3_f32 v216, v216, v69, v70
	s_waitcnt lgkmcnt(5)
	v_mfma_f32_32x32x16_bf16 v[2:17], v[170:173], v[58:61], v[2:17]
	v_max3_f32 v217, v217, v85, v86
	v_max3_f32 v216, v216, v71, v72
	v_max3_f32 v217, v217, v87, v88
	v_max3_f32 v216, v216, v73, v74
	v_max3_f32 v217, v217, v89, v90
	v_max3_f32 v216, v216, v75, v76
	v_max3_f32 v217, v217, v91, v92
	v_max3_f32 v216, v216, v77, v78
	s_waitcnt lgkmcnt(3)
	v_mfma_f32_32x32x16_bf16 v[18:33], v[174:177], v[58:61], v[18:33]
	v_max3_f32 v217, v217, v93, v94
	v_max3_f32 v216, v216, v79, v80
	v_max3_f32 v217, v217, v95, v96
	v_max_f32_e32 v216, v216, v81
	v_max_f32_e32 v217, v217, v97
	v_cmp_lt_f32_e32 vcc, 4.0, v216
	v_cmp_lt_f32_e64 s[28:29], 4.0, v217
	s_or_b64 vcc, vcc, s[28:29]
	s_cbranch_vccz .Lna_nr_c0
	v_max_f32_e32 v216, v216, v217
	v_mov_b32_e32 v217, v216
	s_nop 1
	v_permlane32_swap_b32_e32 v216, v217
	v_max_f32_e32 v215, v216, v217
	s_nop 15
	v_max_f32_e32 v216, v215, v220
	v_exp_f32_e64 v217, -v216
	v_add_f32_e32 v212, v212, v216
	v_and_b32_e32 v217, v217, v221
	v_sub_f32_e32 v66, v66, v216
	v_sub_f32_e32 v67, v67, v216
	v_sub_f32_e32 v68, v68, v216
	v_sub_f32_e32 v69, v69, v216
	v_sub_f32_e32 v70, v70, v216
	v_sub_f32_e32 v71, v71, v216
	v_sub_f32_e32 v72, v72, v216
	v_sub_f32_e32 v73, v73, v216
	v_sub_f32_e32 v74, v74, v216
	v_sub_f32_e32 v75, v75, v216
	v_sub_f32_e32 v76, v76, v216
	v_sub_f32_e32 v77, v77, v216
	v_sub_f32_e32 v78, v78, v216
	v_sub_f32_e32 v79, v79, v216
	v_sub_f32_e32 v80, v80, v216
	v_sub_f32_e32 v81, v81, v216
	v_sub_f32_e32 v82, v82, v216
	v_sub_f32_e32 v83, v83, v216
	v_sub_f32_e32 v84, v84, v216
	v_sub_f32_e32 v85, v85, v216
	v_sub_f32_e32 v86, v86, v216
	v_sub_f32_e32 v87, v87, v216
	v_sub_f32_e32 v88, v88, v216
	v_sub_f32_e32 v89, v89, v216
	v_sub_f32_e32 v90, v90, v216
	v_sub_f32_e32 v91, v91, v216
	v_sub_f32_e32 v92, v92, v216
	v_sub_f32_e32 v93, v93, v216
	v_sub_f32_e32 v94, v94, v216
	v_sub_f32_e32 v95, v95, v216
	v_sub_f32_e32 v96, v96, v216
	v_sub_f32_e32 v97, v97, v216
	v_sub_f32_e32 v114, v114, v216
	v_sub_f32_e32 v115, v115, v216
	v_sub_f32_e32 v116, v116, v216
	v_sub_f32_e32 v117, v117, v216
	v_sub_f32_e32 v118, v118, v216
	v_sub_f32_e32 v119, v119, v216
	v_sub_f32_e32 v120, v120, v216
	v_sub_f32_e32 v121, v121, v216
	v_sub_f32_e32 v122, v122, v216
	v_sub_f32_e32 v123, v123, v216
	v_sub_f32_e32 v124, v124, v216
	v_sub_f32_e32 v125, v125, v216
	v_sub_f32_e32 v126, v126, v216
	v_sub_f32_e32 v127, v127, v216
	v_sub_f32_e32 v128, v128, v216
	v_sub_f32_e32 v129, v129, v216
	v_sub_f32_e32 v130, v130, v216
	v_sub_f32_e32 v131, v131, v216
	v_sub_f32_e32 v132, v132, v216
	v_sub_f32_e32 v133, v133, v216
	v_sub_f32_e32 v134, v134, v216
	v_sub_f32_e32 v135, v135, v216
	v_sub_f32_e32 v136, v136, v216
	v_sub_f32_e32 v137, v137, v216
	v_sub_f32_e32 v138, v138, v216
	v_sub_f32_e32 v139, v139, v216
	v_sub_f32_e32 v140, v140, v216
	v_sub_f32_e32 v141, v141, v216
	v_sub_f32_e32 v142, v142, v216
	v_sub_f32_e32 v143, v143, v216
	v_sub_f32_e32 v144, v144, v216
	v_sub_f32_e32 v145, v145, v216
	v_mul_f32_e32 v213, v213, v217
	v_mul_f32_e32 v214, v214, v217
	v_mul_f32_e32 v2, v2, v217
	v_mul_f32_e32 v3, v3, v217
	v_mul_f32_e32 v4, v4, v217
	v_mul_f32_e32 v5, v5, v217
	v_mul_f32_e32 v6, v6, v217
	v_mul_f32_e32 v7, v7, v217
	v_mul_f32_e32 v8, v8, v217
	v_mul_f32_e32 v9, v9, v217
	v_mul_f32_e32 v10, v10, v217
	v_mul_f32_e32 v11, v11, v217
	v_mul_f32_e32 v12, v12, v217
	v_mul_f32_e32 v13, v13, v217
	v_mul_f32_e32 v14, v14, v217
	v_mul_f32_e32 v15, v15, v217
	v_mul_f32_e32 v16, v16, v217
	v_mul_f32_e32 v17, v17, v217
	v_mul_f32_e32 v18, v18, v217
	v_mul_f32_e32 v19, v19, v217
	v_mul_f32_e32 v20, v20, v217
	v_mul_f32_e32 v21, v21, v217
	v_mul_f32_e32 v22, v22, v217
	v_mul_f32_e32 v23, v23, v217
	v_mul_f32_e32 v24, v24, v217
	v_mul_f32_e32 v25, v25, v217
	v_mul_f32_e32 v26, v26, v217
	v_mul_f32_e32 v27, v27, v217
	v_mul_f32_e32 v28, v28, v217
	v_mul_f32_e32 v29, v29, v217
	v_mul_f32_e32 v30, v30, v217
	v_mul_f32_e32 v31, v31, v217
	v_mul_f32_e32 v32, v32, v217
	v_mul_f32_e32 v33, v33, v217
.Lna_nr_c0:
	s_waitcnt lgkmcnt(0)
	s_barrier
	ds_read_b128 v[146:149], v200 offset:0
	ds_read_b128 v[150:153], v200 offset:4608
	ds_read_b128 v[154:157], v200 offset:32
	ds_read_b128 v[158:161], v200 offset:4640
	v_exp_f32_e32 v66, v66
	v_exp_f32_e32 v67, v67
	v_exp_f32_e32 v68, v68
	v_exp_f32_e32 v69, v69
	s_waitcnt lgkmcnt(2)
	v_mfma_f32_32x32x16_bf16 v[34:49], v[146:149], v[98:101], v[114:129]
	ds_read_b128 v[146:149], v200 offset:64
	v_add_f32_e32 v213, v213, v66
	v_add_f32_e32 v214, v214, v67
	v_add_f32_e32 v213, v213, v68
	v_add_f32_e32 v214, v214, v69
	v_exp_f32_e32 v70, v70
	v_exp_f32_e32 v71, v71
	v_mfma_f32_32x32x16_bf16 v[50:65], v[150:153], v[98:101], v[130:145]
	ds_read_b128 v[150:153], v200 offset:4672
	v_exp_f32_e32 v72, v72
	v_exp_f32_e32 v73, v73
	v_add_f32_e32 v213, v213, v70
	v_add_f32_e32 v214, v214, v71
	v_add_f32_e32 v213, v213, v72
	s_waitcnt lgkmcnt(2)
	v_mfma_f32_32x32x16_bf16 v[34:49], v[154:157], v[102:105], v[34:49]
	ds_read_b128 v[154:157], v200 offset:96
	v_add_f32_e32 v214, v214, v73
	v_cvt_pk_bf16_f32 v66, v66, v67
	v_cvt_pk_bf16_f32 v67, v68, v69
	v_cvt_pk_bf16_f32 v68, v70, v71
	v_cvt_pk_bf16_f32 v69, v72, v73
	v_exp_f32_e32 v74, v74
	v_exp_f32_e32 v75, v75
	v_mfma_f32_32x32x16_bf16 v[50:65], v[158:161], v[102:105], v[50:65]
	ds_read_b128 v[158:161], v200 offset:4704
	v_exp_f32_e32 v76, v76
	v_exp_f32_e32 v77, v77
	v_add_f32_e32 v213, v213, v74
	v_add_f32_e32 v214, v214, v75
	v_add_f32_e32 v213, v213, v76
	s_waitcnt lgkmcnt(2)
	v_mfma_f32_32x32x16_bf16 v[34:49], v[146:149], v[106:109], v[34:49]
	ds_read_b64 v[162:163], v202 offset:8704
	ds_read_b64 v[164:165], v202 offset:8720
	v_add_f32_e32 v214, v214, v77
	v_exp_f32_e32 v78, v78
	v_exp_f32_e32 v79, v79
	v_exp_f32_e32 v80, v80
	v_mfma_f32_32x32x16_bf16 v[50:65], v[150:153], v[106:109], v[50:65]
	ds_read_b64 v[166:167], v202 offset:13056
	ds_read_b64 v[168:169], v202 offset:13072
	v_exp_f32_e32 v81, v81
	v_add_f32_e32 v213, v213, v78
	v_add_f32_e32 v214, v214, v79
	v_add_f32_e32 v213, v213, v80
	v_add_f32_e32 v214, v214, v81
	v_cvt_pk_bf16_f32 v74, v74, v75
	v_cvt_pk_bf16_f32 v75, v76, v77
	s_waitcnt lgkmcnt(4)
	v_mfma_f32_32x32x16_bf16 v[34:49], v[154:157], v[110:113], v[34:49]
	ds_read_b64 v[170:171], v202 offset:8736
	ds_read_b64 v[172:173], v202 offset:8752
	v_cvt_pk_bf16_f32 v76, v78, v79
	v_cvt_pk_bf16_f32 v77, v80, v81
	v_exp_f32_e32 v82, v82
	v_exp_f32_e32 v83, v83
	v_exp_f32_e32 v84, v84
	v_mfma_f32_32x32x16_bf16 v[50:65], v[158:161], v[110:113], v[50:65]
	ds_read_b64 v[174:175], v202 offset:13088
	ds_read_b64 v[176:177], v202 offset:13104
	v_exp_f32_e32 v85, v85
	v_add_f32_e32 v213, v213, v82
	v_add_f32_e32 v214, v214, v83
	v_add_f32_e32 v213, v213, v84
	v_add_f32_e32 v214, v214, v85
	v_exp_f32_e32 v86, v86
	s_waitcnt lgkmcnt(6)
	v_mfma_f32_32x32x16_bf16 v[2:17], v[162:165], v[66:69], v[2:17]
	ds_read_b64 v[162:163], v202 offset:8768
	ds_read_b64 v[164:165], v202 offset:8784
	v_exp_f32_e32 v87, v87
	v_exp_f32_e32 v88, v88
	v_exp_f32_e32 v89, v89
	v_add_f32_e32 v213, v213, v86
	s_waitcnt lgkmcnt(6)
	v_mfma_f32_32x32x16_bf16 v[18:33], v[166:169], v[66:69], v[18:33]
	ds_read_b64 v[166:167], v202 offset:13120
	ds_read_b64 v[168:169], v202 offset:13136
	v_add_f32_e32 v214, v214, v87
	v_add_f32_e32 v213, v213, v88
	v_add_f32_e32 v214, v214, v89
	v_cvt_pk_bf16_f32 v82, v82, v83
	v_cvt_pk_bf16_f32 v83, v84, v85
	v_cvt_pk_bf16_f32 v84, v86, v87
	v_cvt_pk_bf16_f32 v85, v88, v89
	v_exp_f32_e32 v90, v90
	s_waitcnt lgkmcnt(6)
	v_mfma_f32_32x32x16_bf16 v[2:17], v[170:173], v[74:77], v[2:17]
	ds_read_b64 v[170:171], v202 offset:8800
	ds_read_b64 v[172:173], v202 offset:8816
	v_exp_f32_e32 v91, v91
	v_exp_f32_e32 v92, v92
	v_exp_f32_e32 v93, v93
	s_waitcnt lgkmcnt(6)
	v_mfma_f32_32x32x16_bf16 v[18:33], v[174:177], v[74:77], v[18:33]
	ds_read_b64 v[174:175], v202 offset:13152
	ds_read_b64 v[176:177], v202 offset:13168
	s_waitcnt vmcnt(1)
	ds_write_b128 v204, v[230:233] offset:9216
	ds_write_b64 v205, v[234:235] offset:0
	ds_write_b64 v205, v[236:237] offset:8
	v_add_f32_e32 v213, v213, v90
	v_add_f32_e32 v214, v214, v91
	v_add_f32_e32 v213, v213, v92
	v_add_f32_e32 v214, v214, v93
	v_exp_f32_e32 v94, v94
	v_exp_f32_e32 v95, v95
	s_waitcnt lgkmcnt(9)
	v_mfma_f32_32x32x16_bf16 v[2:17], v[162:165], v[82:85], v[2:17]
	v_exp_f32_e32 v96, v96
	v_exp_f32_e32 v97, v97
	v_add_f32_e32 v213, v213, v94
	v_add_f32_e32 v214, v214, v95
	v_add_f32_e32 v213, v213, v96
	v_add_f32_e32 v214, v214, v97
	s_waitcnt lgkmcnt(7)
	v_mfma_f32_32x32x16_bf16 v[18:33], v[166:169], v[82:85], v[18:33]
	v_cvt_pk_bf16_f32 v90, v90, v91
	v_cvt_pk_bf16_f32 v91, v92, v93
	v_cvt_pk_bf16_f32 v92, v94, v95
	v_cvt_pk_bf16_f32 v93, v96, v97
	v_max3_f32 v216, v34, v35, v36
	v_max3_f32 v217, v50, v51, v52
	v_max3_f32 v216, v216, v37, v38
	s_waitcnt lgkmcnt(5)
	v_mfma_f32_32x32x16_bf16 v[2:17], v[170:173], v[90:93], v[2:17]
	v_max3_f32 v217, v217, v53, v54
	v_max3_f32 v216, v216, v39, v40
	v_max3_f32 v217, v217, v55, v56
	v_max3_f32 v216, v216, v41, v42
	v_max3_f32 v217, v217, v57, v58
	v_max3_f32 v216, v216, v43, v44
	v_max3_f32 v217, v217, v59, v60
	v_max3_f32 v216, v216, v45, v46
	s_waitcnt lgkmcnt(3)
	v_mfma_f32_32x32x16_bf16 v[18:33], v[174:177], v[90:93], v[18:33]
	v_max3_f32 v217, v217, v61, v62
	v_max3_f32 v216, v216, v47, v48
	v_max3_f32 v217, v217, v63, v64
	v_max_f32_e32 v216, v216, v49
	v_max_f32_e32 v217, v217, v65
	v_cmp_lt_f32_e32 vcc, 4.0, v216
	v_cmp_lt_f32_e64 s[28:29], 4.0, v217
	s_or_b64 vcc, vcc, s[28:29]
	s_cbranch_vccz .Lna_nr_c1
	v_max_f32_e32 v216, v216, v217
	v_mov_b32_e32 v217, v216
	s_nop 1
	v_permlane32_swap_b32_e32 v216, v217
	v_max_f32_e32 v215, v216, v217
	s_nop 15
	v_max_f32_e32 v216, v215, v220
	v_exp_f32_e64 v217, -v216
	v_add_f32_e32 v212, v212, v216
	v_and_b32_e32 v217, v217, v221
	v_sub_f32_e32 v34, v34, v216
	v_sub_f32_e32 v35, v35, v216
	v_sub_f32_e32 v36, v36, v216
	v_sub_f32_e32 v37, v37, v216
	v_sub_f32_e32 v38, v38, v216
	v_sub_f32_e32 v39, v39, v216
	v_sub_f32_e32 v40, v40, v216
	v_sub_f32_e32 v41, v41, v216
	v_sub_f32_e32 v42, v42, v216
	v_sub_f32_e32 v43, v43, v216
	v_sub_f32_e32 v44, v44, v216
	v_sub_f32_e32 v45, v45, v216
	v_sub_f32_e32 v46, v46, v216
	v_sub_f32_e32 v47, v47, v216
	v_sub_f32_e32 v48, v48, v216
	v_sub_f32_e32 v49, v49, v216
	v_sub_f32_e32 v50, v50, v216
	v_sub_f32_e32 v51, v51, v216
	v_sub_f32_e32 v52, v52, v216
	v_sub_f32_e32 v53, v53, v216
	v_sub_f32_e32 v54, v54, v216
	v_sub_f32_e32 v55, v55, v216
	v_sub_f32_e32 v56, v56, v216
	v_sub_f32_e32 v57, v57, v216
	v_sub_f32_e32 v58, v58, v216
	v_sub_f32_e32 v59, v59, v216
	v_sub_f32_e32 v60, v60, v216
	v_sub_f32_e32 v61, v61, v216
	v_sub_f32_e32 v62, v62, v216
	v_sub_f32_e32 v63, v63, v216
	v_sub_f32_e32 v64, v64, v216
	v_sub_f32_e32 v65, v65, v216
	v_sub_f32_e32 v114, v114, v216
	v_sub_f32_e32 v115, v115, v216
	v_sub_f32_e32 v116, v116, v216
	v_sub_f32_e32 v117, v117, v216
	v_sub_f32_e32 v118, v118, v216
	v_sub_f32_e32 v119, v119, v216
	v_sub_f32_e32 v120, v120, v216
	v_sub_f32_e32 v121, v121, v216
	v_sub_f32_e32 v122, v122, v216
	v_sub_f32_e32 v123, v123, v216
	v_sub_f32_e32 v124, v124, v216
	v_sub_f32_e32 v125, v125, v216
	v_sub_f32_e32 v126, v126, v216
	v_sub_f32_e32 v127, v127, v216
	v_sub_f32_e32 v128, v128, v216
	v_sub_f32_e32 v129, v129, v216
	v_sub_f32_e32 v130, v130, v216
	v_sub_f32_e32 v131, v131, v216
	v_sub_f32_e32 v132, v132, v216
	v_sub_f32_e32 v133, v133, v216
	v_sub_f32_e32 v134, v134, v216
	v_sub_f32_e32 v135, v135, v216
	v_sub_f32_e32 v136, v136, v216
	v_sub_f32_e32 v137, v137, v216
	v_sub_f32_e32 v138, v138, v216
	v_sub_f32_e32 v139, v139, v216
	v_sub_f32_e32 v140, v140, v216
	v_sub_f32_e32 v141, v141, v216
	v_sub_f32_e32 v142, v142, v216
	v_sub_f32_e32 v143, v143, v216
	v_sub_f32_e32 v144, v144, v216
	v_sub_f32_e32 v145, v145, v216
	v_mul_f32_e32 v213, v213, v217
	v_mul_f32_e32 v214, v214, v217
	v_mul_f32_e32 v2, v2, v217
	v_mul_f32_e32 v3, v3, v217
	v_mul_f32_e32 v4, v4, v217
	v_mul_f32_e32 v5, v5, v217
	v_mul_f32_e32 v6, v6, v217
	v_mul_f32_e32 v7, v7, v217
	v_mul_f32_e32 v8, v8, v217
	v_mul_f32_e32 v9, v9, v217
	v_mul_f32_e32 v10, v10, v217
	v_mul_f32_e32 v11, v11, v217
	v_mul_f32_e32 v12, v12, v217
	v_mul_f32_e32 v13, v13, v217
	v_mul_f32_e32 v14, v14, v217
	v_mul_f32_e32 v15, v15, v217
	v_mul_f32_e32 v16, v16, v217
	v_mul_f32_e32 v17, v17, v217
	v_mul_f32_e32 v18, v18, v217
	v_mul_f32_e32 v19, v19, v217
	v_mul_f32_e32 v20, v20, v217
	v_mul_f32_e32 v21, v21, v217
	v_mul_f32_e32 v22, v22, v217
	v_mul_f32_e32 v23, v23, v217
	v_mul_f32_e32 v24, v24, v217
	v_mul_f32_e32 v25, v25, v217
	v_mul_f32_e32 v26, v26, v217
	v_mul_f32_e32 v27, v27, v217
	v_mul_f32_e32 v28, v28, v217
	v_mul_f32_e32 v29, v29, v217
	v_mul_f32_e32 v30, v30, v217
	v_mul_f32_e32 v31, v31, v217
	v_mul_f32_e32 v32, v32, v217
	v_mul_f32_e32 v33, v33, v217
.Lna_nr_c1:
	s_waitcnt lgkmcnt(0)
	s_barrier
	ds_read_b128 v[146:149], v200 offset:9216
	ds_read_b128 v[150:153], v200 offset:13824
	ds_read_b128 v[154:157], v200 offset:9248
	ds_read_b128 v[158:161], v200 offset:13856
	v_exp_f32_e32 v34, v34
	v_exp_f32_e32 v35, v35
	v_exp_f32_e32 v36, v36
	v_exp_f32_e32 v37, v37
	s_waitcnt lgkmcnt(2)
	v_mfma_f32_32x32x16_bf16 v[66:81], v[146:149], v[98:101], v[114:129]
	ds_read_b128 v[146:149], v200 offset:9280
	v_add_f32_e32 v213, v213, v34
	v_add_f32_e32 v214, v214, v35
	v_add_f32_e32 v213, v213, v36
	v_add_f32_e32 v214, v214, v37
	v_exp_f32_e32 v38, v38
	v_exp_f32_e32 v39, v39
	v_mfma_f32_32x32x16_bf16 v[82:97], v[150:153], v[98:101], v[130:145]
	ds_read_b128 v[150:153], v200 offset:13888
	v_exp_f32_e32 v40, v40
	v_exp_f32_e32 v41, v41
	v_add_f32_e32 v213, v213, v38
	v_add_f32_e32 v214, v214, v39
	v_add_f32_e32 v213, v213, v40
	s_waitcnt lgkmcnt(2)
	v_mfma_f32_32x32x16_bf16 v[66:81], v[154:157], v[102:105], v[66:81]
	ds_read_b128 v[154:157], v200 offset:9312
	v_add_f32_e32 v214, v214, v41
	v_cvt_pk_bf16_f32 v34, v34, v35
	v_cvt_pk_bf16_f32 v35, v36, v37
	v_cvt_pk_bf16_f32 v36, v38, v39
	v_cvt_pk_bf16_f32 v37, v40, v41
	v_exp_f32_e32 v42, v42
	v_exp_f32_e32 v43, v43
	v_mfma_f32_32x32x16_bf16 v[82:97], v[158:161], v[102:105], v[82:97]
	ds_read_b128 v[158:161], v200 offset:13920
	v_exp_f32_e32 v44, v44
	v_exp_f32_e32 v45, v45
	v_add_f32_e32 v213, v213, v42
	v_add_f32_e32 v214, v214, v43
	v_add_f32_e32 v213, v213, v44
	s_waitcnt lgkmcnt(2)
	v_mfma_f32_32x32x16_bf16 v[66:81], v[146:149], v[106:109], v[66:81]
	ds_read_b64 v[162:163], v202 offset:0
	ds_read_b64 v[164:165], v202 offset:16
	v_add_f32_e32 v214, v214, v45
	v_exp_f32_e32 v46, v46
	v_exp_f32_e32 v47, v47
	v_exp_f32_e32 v48, v48
	v_mfma_f32_32x32x16_bf16 v[82:97], v[150:153], v[106:109], v[82:97]
	ds_read_b64 v[166:167], v202 offset:4352
	ds_read_b64 v[168:169], v202 offset:4368
	v_exp_f32_e32 v49, v49
	v_add_f32_e32 v213, v213, v46
	v_add_f32_e32 v214, v214, v47
	v_add_f32_e32 v213, v213, v48
	v_add_f32_e32 v214, v214, v49
	v_cvt_pk_bf16_f32 v42, v42, v43
	v_cvt_pk_bf16_f32 v43, v44, v45
	s_waitcnt lgkmcnt(4)
	v_mfma_f32_32x32x16_bf16 v[66:81], v[154:157], v[110:113], v[66:81]
	ds_read_b64 v[170:171], v202 offset:32
	ds_read_b64 v[172:173], v202 offset:48
	v_cvt_pk_bf16_f32 v44, v46, v47
	v_cvt_pk_bf16_f32 v45, v48, v49
	v_exp_f32_e32 v50, v50
	v_exp_f32_e32 v51, v51
	v_exp_f32_e32 v52, v52
	v_mfma_f32_32x32x16_bf16 v[82:97], v[158:161], v[110:113], v[82:97]
	ds_read_b64 v[174:175], v202 offset:4384
	ds_read_b64 v[176:177], v202 offset:4400
	v_exp_f32_e32 v53, v53
	v_add_f32_e32 v213, v213, v50
	v_add_f32_e32 v214, v214, v51
	v_add_f32_e32 v213, v213, v52
	v_add_f32_e32 v214, v214, v53
	v_exp_f32_e32 v54, v54
	s_waitcnt lgkmcnt(6)
	v_mfma_f32_32x32x16_bf16 v[2:17], v[162:165], v[34:37], v[2:17]
	ds_read_b64 v[162:163], v202 offset:64
	ds_read_b64 v[164:165], v202 offset:80
	v_exp_f32_e32 v55, v55
	v_exp_f32_e32 v56, v56
	v_exp_f32_e32 v57, v57
	v_add_f32_e32 v213, v213, v54
	s_waitcnt lgkmcnt(6)
	v_mfma_f32_32x32x16_bf16 v[18:33], v[166:169], v[34:37], v[18:33]
	ds_read_b64 v[166:167], v202 offset:4416
	ds_read_b64 v[168:169], v202 offset:4432
	v_add_f32_e32 v214, v214, v55
	v_add_f32_e32 v213, v213, v56
	v_add_f32_e32 v214, v214, v57
	v_cvt_pk_bf16_f32 v50, v50, v51
	v_cvt_pk_bf16_f32 v51, v52, v53
	v_cvt_pk_bf16_f32 v52, v54, v55
	v_cvt_pk_bf16_f32 v53, v56, v57
	v_exp_f32_e32 v58, v58
	s_waitcnt lgkmcnt(6)
	v_mfma_f32_32x32x16_bf16 v[2:17], v[170:173], v[42:45], v[2:17]
	ds_read_b64 v[170:171], v202 offset:96
	ds_read_b64 v[172:173], v202 offset:112
	v_exp_f32_e32 v59, v59
	v_exp_f32_e32 v60, v60
	v_exp_f32_e32 v61, v61
	s_waitcnt lgkmcnt(6)
	v_mfma_f32_32x32x16_bf16 v[18:33], v[174:177], v[42:45], v[18:33]
	ds_read_b64 v[174:175], v202 offset:4448
	ds_read_b64 v[176:177], v202 offset:4464
	s_waitcnt vmcnt(0)
	ds_write_b64 v205, v[192:193] offset:8704
	ds_write_b64 v205, v[194:195] offset:8712
	v_add_f32_e32 v213, v213, v58
	v_add_f32_e32 v214, v214, v59
	v_add_f32_e32 v213, v213, v60
	v_add_f32_e32 v214, v214, v61
	v_exp_f32_e32 v62, v62
	v_exp_f32_e32 v63, v63
	s_waitcnt lgkmcnt(8)
	v_mfma_f32_32x32x16_bf16 v[2:17], v[162:165], v[50:53], v[2:17]
	v_exp_f32_e32 v64, v64
	v_exp_f32_e32 v65, v65
	v_add_f32_e32 v213, v213, v62
	v_add_f32_e32 v214, v214, v63
	v_add_f32_e32 v213, v213, v64
	v_add_f32_e32 v214, v214, v65
	s_waitcnt lgkmcnt(6)
	v_mfma_f32_32x32x16_bf16 v[18:33], v[166:169], v[50:53], v[18:33]
	v_cvt_pk_bf16_f32 v58, v58, v59
	v_cvt_pk_bf16_f32 v59, v60, v61
	v_cvt_pk_bf16_f32 v60, v62, v63
	v_cvt_pk_bf16_f32 v61, v64, v65
	v_max3_f32 v216, v66, v67, v68
	v_max3_f32 v217, v82, v83, v84
	v_max3_f32 v216, v216, v69, v70
	s_waitcnt lgkmcnt(4)
	v_mfma_f32_32x32x16_bf16 v[2:17], v[170:173], v[58:61], v[2:17]
	v_max3_f32 v217, v217, v85, v86
	v_max3_f32 v216, v216, v71, v72
	v_max3_f32 v217, v217, v87, v88
	v_max3_f32 v216, v216, v73, v74
	v_max3_f32 v217, v217, v89, v90
	v_max3_f32 v216, v216, v75, v76
	v_max3_f32 v217, v217, v91, v92
	v_max3_f32 v216, v216, v77, v78
	s_waitcnt lgkmcnt(2)
	v_mfma_f32_32x32x16_bf16 v[18:33], v[174:177], v[58:61], v[18:33]
	v_max3_f32 v217, v217, v93, v94
	v_max3_f32 v216, v216, v79, v80
	v_max3_f32 v217, v217, v95, v96
	v_max_f32_e32 v216, v216, v81
	v_max_f32_e32 v217, v217, v97
	v_cmp_lt_f32_e32 vcc, 4.0, v216
	v_cmp_lt_f32_e64 s[28:29], 4.0, v217
	s_or_b64 vcc, vcc, s[28:29]
	s_cbranch_vccz .Lna_nr_c2
	v_max_f32_e32 v216, v216, v217
	v_mov_b32_e32 v217, v216
	s_nop 1
	v_permlane32_swap_b32_e32 v216, v217
	v_max_f32_e32 v215, v216, v217
	s_nop 15
	v_max_f32_e32 v216, v215, v220
	v_exp_f32_e64 v217, -v216
	v_add_f32_e32 v212, v212, v216
	v_and_b32_e32 v217, v217, v221
	v_sub_f32_e32 v66, v66, v216
	v_sub_f32_e32 v67, v67, v216
	v_sub_f32_e32 v68, v68, v216
	v_sub_f32_e32 v69, v69, v216
	v_sub_f32_e32 v70, v70, v216
	v_sub_f32_e32 v71, v71, v216
	v_sub_f32_e32 v72, v72, v216
	v_sub_f32_e32 v73, v73, v216
	v_sub_f32_e32 v74, v74, v216
	v_sub_f32_e32 v75, v75, v216
	v_sub_f32_e32 v76, v76, v216
	v_sub_f32_e32 v77, v77, v216
	v_sub_f32_e32 v78, v78, v216
	v_sub_f32_e32 v79, v79, v216
	v_sub_f32_e32 v80, v80, v216
	v_sub_f32_e32 v81, v81, v216
	v_sub_f32_e32 v82, v82, v216
	v_sub_f32_e32 v83, v83, v216
	v_sub_f32_e32 v84, v84, v216
	v_sub_f32_e32 v85, v85, v216
	v_sub_f32_e32 v86, v86, v216
	v_sub_f32_e32 v87, v87, v216
	v_sub_f32_e32 v88, v88, v216
	v_sub_f32_e32 v89, v89, v216
	v_sub_f32_e32 v90, v90, v216
	v_sub_f32_e32 v91, v91, v216
	v_sub_f32_e32 v92, v92, v216
	v_sub_f32_e32 v93, v93, v216
	v_sub_f32_e32 v94, v94, v216
	v_sub_f32_e32 v95, v95, v216
	v_sub_f32_e32 v96, v96, v216
	v_sub_f32_e32 v97, v97, v216
	v_sub_f32_e32 v114, v114, v216
	v_sub_f32_e32 v115, v115, v216
	v_sub_f32_e32 v116, v116, v216
	v_sub_f32_e32 v117, v117, v216
	v_sub_f32_e32 v118, v118, v216
	v_sub_f32_e32 v119, v119, v216
	v_sub_f32_e32 v120, v120, v216
	v_sub_f32_e32 v121, v121, v216
	v_sub_f32_e32 v122, v122, v216
	v_sub_f32_e32 v123, v123, v216
	v_sub_f32_e32 v124, v124, v216
	v_sub_f32_e32 v125, v125, v216
	v_sub_f32_e32 v126, v126, v216
	v_sub_f32_e32 v127, v127, v216
	v_sub_f32_e32 v128, v128, v216
	v_sub_f32_e32 v129, v129, v216
	v_sub_f32_e32 v130, v130, v216
	v_sub_f32_e32 v131, v131, v216
	v_sub_f32_e32 v132, v132, v216
	v_sub_f32_e32 v133, v133, v216
	v_sub_f32_e32 v134, v134, v216
	v_sub_f32_e32 v135, v135, v216
	v_sub_f32_e32 v136, v136, v216
	v_sub_f32_e32 v137, v137, v216
	v_sub_f32_e32 v138, v138, v216
	v_sub_f32_e32 v139, v139, v216
	v_sub_f32_e32 v140, v140, v216
	v_sub_f32_e32 v141, v141, v216
	v_sub_f32_e32 v142, v142, v216
	v_sub_f32_e32 v143, v143, v216
	v_sub_f32_e32 v144, v144, v216
	v_sub_f32_e32 v145, v145, v216
	v_mul_f32_e32 v213, v213, v217
	v_mul_f32_e32 v214, v214, v217
	v_mul_f32_e32 v2, v2, v217
	v_mul_f32_e32 v3, v3, v217
	v_mul_f32_e32 v4, v4, v217
	v_mul_f32_e32 v5, v5, v217
	v_mul_f32_e32 v6, v6, v217
	v_mul_f32_e32 v7, v7, v217
	v_mul_f32_e32 v8, v8, v217
	v_mul_f32_e32 v9, v9, v217
	v_mul_f32_e32 v10, v10, v217
	v_mul_f32_e32 v11, v11, v217
	v_mul_f32_e32 v12, v12, v217
	v_mul_f32_e32 v13, v13, v217
	v_mul_f32_e32 v14, v14, v217
	v_mul_f32_e32 v15, v15, v217
	v_mul_f32_e32 v16, v16, v217
	v_mul_f32_e32 v17, v17, v217
	v_mul_f32_e32 v18, v18, v217
	v_mul_f32_e32 v19, v19, v217
	v_mul_f32_e32 v20, v20, v217
	v_mul_f32_e32 v21, v21, v217
	v_mul_f32_e32 v22, v22, v217
	v_mul_f32_e32 v23, v23, v217
	v_mul_f32_e32 v24, v24, v217
	v_mul_f32_e32 v25, v25, v217
	v_mul_f32_e32 v26, v26, v217
	v_mul_f32_e32 v27, v27, v217
	v_mul_f32_e32 v28, v28, v217
	v_mul_f32_e32 v29, v29, v217
	v_mul_f32_e32 v30, v30, v217
	v_mul_f32_e32 v31, v31, v217
	v_mul_f32_e32 v32, v32, v217
	v_mul_f32_e32 v33, v33, v217
